# K-loop segment edges: setprio 1 ahead of the opening barrier, satisfied lgkmcnt wait removed, setprio 0 behind the closing barrier
# speedup vs baseline: 1.0097x; 1.0021x over previous
.LBB0_231:
	s_ashr_i32 s77, s76, 31
	s_lshl_b64 s[66:67], s[76:77], 19
	s_add_u32 s80, s12, s66
	s_addc_u32 s81, s13, s67
	s_and_b64 s[66:67], s[78:79], exec
	s_cselect_b32 s66, s81, s85
	s_cselect_b32 s67, s80, s84
	s_ashr_i32 s75, s74, 31
	s_lshl_b64 s[68:69], s[74:75], 19
	s_add_u32 s82, s5, s68
	s_addc_u32 s83, s20, s69
	s_and_b64 s[68:69], s[78:79], exec
	s_cselect_b32 s68, s83, s87
	s_cselect_b32 s69, s82, s86
	s_add_u32 s84, s84, 0x40080
	s_addc_u32 s85, s85, 0
	s_add_u32 s75, s86, 0x100
	s_addc_u32 s77, s87, 0
	s_mov_b32 s90, -2
	s_waitcnt vmcnt(0)
	s_add_u32 s0, s84, 0xfffc0080
	s_addc_u32 s86, s85, -1
	s_add_i32 s96, 0, 0x10000
	s_cmp_eq_u32 s90, 12
	s_cselect_b32 s89, s66, s86
	s_cselect_b32 s88, s67, s0
	s_cselect_b32 s87, s68, s77
	s_cselect_b32 s86, s69, s75
	s_add_i32 s0, 0, 0x14000
	v_add_u32_e32 v160, s96, v145
	v_add_u32_e32 v176, s0, v145
	ds_read_b128 v[140:143], v160
	ds_read_b128 v[152:155], v160 offset:1024
	ds_read_b128 v[156:159], v160 offset:2048
	ds_read_b128 v[160:163], v160 offset:3072
	ds_read_b128 v[164:167], v176
	ds_read_b128 v[168:171], v176 offset:1024
	ds_read_b128 v[172:175], v176 offset:2048
	ds_read_b128 v[176:179], v176 offset:3072
	v_lshl_add_u64 v[180:181], s[84:85], 0, v[136:137]
	s_add_i32 m0, s22, 0xc000
	ds_read_b128 v[188:191], v151
	ds_read_b128 v[220:223], v151 offset:1024
	ds_read_b128 v[224:227], v151 offset:2048
	ds_read_b128 v[228:231], v151 offset:3072
	ds_read_b128 v[232:235], v151 offset:4096
	ds_read_b128 v[236:239], v151 offset:5120
	ds_read_b128 v[240:243], v151 offset:6144
	ds_read_b128 v[244:247], v151 offset:7168
	global_load_lds_dwordx4 v[180:181], off
	v_lshl_add_u64 v[180:181], s[84:85], 0, v[138:139]
	s_add_i32 m0, s22, 0xe000
	s_nop 0
	global_load_lds_dwordx4 v[180:181], off
	s_waitcnt vmcnt(8)
	s_waitcnt lgkmcnt(0)
	s_setprio 1
	s_barrier
	v_mfma_f32_16x16x32_bf16 v[128:131], v[140:143], v[188:191], 0
	v_mfma_f32_16x16x32_bf16 v[124:127], v[156:159], v[188:191], 0
	v_mfma_f32_16x16x32_bf16 v[112:115], v[140:143], v[224:227], 0
	v_mfma_f32_16x16x32_bf16 v[108:111], v[156:159], v[224:227], 0
	v_mfma_f32_16x16x32_bf16 v[92:95], v[140:143], v[232:235], 0
	v_mfma_f32_16x16x32_bf16 v[88:91], v[156:159], v[232:235], 0
	v_mfma_f32_16x16x32_bf16 v[76:79], v[140:143], v[240:243], 0
	v_mfma_f32_16x16x32_bf16 v[72:75], v[156:159], v[240:243], 0
	v_mfma_f32_16x16x32_bf16 v[128:131], v[152:155], v[220:223], v[128:131]
	v_mfma_f32_16x16x32_bf16 v[124:127], v[160:163], v[220:223], v[124:127]
	v_mfma_f32_16x16x32_bf16 v[112:115], v[152:155], v[228:231], v[112:115]
	v_mfma_f32_16x16x32_bf16 v[108:111], v[160:163], v[228:231], v[108:111]
	v_mfma_f32_16x16x32_bf16 v[92:95], v[152:155], v[236:239], v[92:95]
	v_mfma_f32_16x16x32_bf16 v[88:91], v[160:163], v[236:239], v[88:91]
	v_mfma_f32_16x16x32_bf16 v[76:79], v[152:155], v[244:247], v[76:79]
	v_mfma_f32_16x16x32_bf16 v[72:75], v[160:163], v[244:247], v[72:75]
	v_mfma_f32_16x16x32_bf16 v[120:123], v[164:167], v[188:191], 0
	v_mfma_f32_16x16x32_bf16 v[116:119], v[172:175], v[188:191], 0
	v_mfma_f32_16x16x32_bf16 v[104:107], v[164:167], v[224:227], 0
	v_mfma_f32_16x16x32_bf16 v[100:103], v[172:175], v[224:227], 0
	v_mfma_f32_16x16x32_bf16 v[84:87], v[164:167], v[232:235], 0
	v_mfma_f32_16x16x32_bf16 v[80:83], v[172:175], v[232:235], 0
	v_mfma_f32_16x16x32_bf16 v[68:71], v[164:167], v[240:243], 0
	v_mfma_f32_16x16x32_bf16 v[64:67], v[172:175], v[240:243], 0
	v_mfma_f32_16x16x32_bf16 v[120:123], v[168:171], v[220:223], v[120:123]
	v_mfma_f32_16x16x32_bf16 v[116:119], v[176:179], v[220:223], v[116:119]
	v_mfma_f32_16x16x32_bf16 v[104:107], v[168:171], v[228:231], v[104:107]
	v_mfma_f32_16x16x32_bf16 v[100:103], v[176:179], v[228:231], v[100:103]
	v_mfma_f32_16x16x32_bf16 v[84:87], v[168:171], v[236:239], v[84:87]
	v_mfma_f32_16x16x32_bf16 v[80:83], v[176:179], v[236:239], v[80:83]
	v_mfma_f32_16x16x32_bf16 v[68:71], v[168:171], v[244:247], v[68:71]
	v_mfma_f32_16x16x32_bf16 v[64:67], v[176:179], v[244:247], v[64:67]
	s_barrier
	s_setprio 0
	s_add_i32 s96, s96, s1
	v_lshl_add_u64 v[180:181], s[86:87], 0, v[98:99]
	s_mov_b32 m0, s96
	ds_read_b128 v[188:191], v151 offset:16384
	ds_read_b128 v[220:223], v151 offset:17408
	ds_read_b128 v[224:227], v151 offset:18432
	ds_read_b128 v[228:231], v151 offset:19456
	ds_read_b128 v[232:235], v151 offset:20480
	ds_read_b128 v[236:239], v151 offset:21504
	ds_read_b128 v[240:243], v151 offset:22528
	ds_read_b128 v[244:247], v151 offset:23552
	global_load_lds_dwordx4 v[180:181], off
	s_add_i32 m0, s96, 0x2000
	s_add_u32 s96, s86, 0x40000
	v_lshl_add_u64 v[192:193], s[86:87], 0, v[134:135]
	s_addc_u32 s97, s87, 0
	s_add_i32 s0, s0, s1
	global_load_lds_dwordx4 v[192:193], off
	v_lshl_add_u64 v[248:249], s[96:97], 0, v[98:99]
	s_mov_b32 m0, s0
	v_lshl_add_u64 v[250:251], s[88:89], 0, v[132:133]
	global_load_lds_dwordx4 v[248:249], off
	v_lshl_add_u64 v[248:249], s[96:97], 0, v[134:135]
	s_add_i32 m0, s0, 0x2000
	s_nop 0
	global_load_lds_dwordx4 v[248:249], off
	v_lshl_add_u64 v[248:249], s[88:89], 0, v[96:97]
	s_mov_b32 m0, s22
	s_nop 0
	global_load_lds_dwordx4 v[248:249], off
	s_mov_b32 m0, s23
	s_nop 0
	global_load_lds_dwordx4 v[250:251], off
	s_waitcnt vmcnt(8)
	s_waitcnt lgkmcnt(0)
	s_setprio 1
	s_barrier
	v_mfma_f32_16x16x32_bf16 v[60:63], v[140:143], v[188:191], 0
	v_mfma_f32_16x16x32_bf16 v[56:59], v[156:159], v[188:191], 0
	v_mfma_f32_16x16x32_bf16 v[44:47], v[140:143], v[224:227], 0
	v_mfma_f32_16x16x32_bf16 v[40:43], v[156:159], v[224:227], 0
	v_mfma_f32_16x16x32_bf16 v[28:31], v[140:143], v[232:235], 0
	v_mfma_f32_16x16x32_bf16 v[24:27], v[156:159], v[232:235], 0
	v_mfma_f32_16x16x32_bf16 v[12:15], v[140:143], v[240:243], 0
	v_mfma_f32_16x16x32_bf16 v[8:11], v[156:159], v[240:243], 0
	v_mfma_f32_16x16x32_bf16 v[60:63], v[152:155], v[220:223], v[60:63]
	v_mfma_f32_16x16x32_bf16 v[56:59], v[160:163], v[220:223], v[56:59]
	v_mfma_f32_16x16x32_bf16 v[44:47], v[152:155], v[228:231], v[44:47]
	v_mfma_f32_16x16x32_bf16 v[40:43], v[160:163], v[228:231], v[40:43]
	v_mfma_f32_16x16x32_bf16 v[28:31], v[152:155], v[236:239], v[28:31]
	v_mfma_f32_16x16x32_bf16 v[24:27], v[160:163], v[236:239], v[24:27]
	v_mfma_f32_16x16x32_bf16 v[12:15], v[152:155], v[244:247], v[12:15]
	v_mfma_f32_16x16x32_bf16 v[8:11], v[160:163], v[244:247], v[8:11]
	v_mfma_f32_16x16x32_bf16 v[52:55], v[164:167], v[188:191], 0
	v_mfma_f32_16x16x32_bf16 v[48:51], v[172:175], v[188:191], 0
	v_mfma_f32_16x16x32_bf16 v[36:39], v[164:167], v[224:227], 0
	v_mfma_f32_16x16x32_bf16 v[32:35], v[172:175], v[224:227], 0
	v_mfma_f32_16x16x32_bf16 v[20:23], v[164:167], v[232:235], 0
	v_mfma_f32_16x16x32_bf16 v[16:19], v[172:175], v[232:235], 0
	v_mfma_f32_16x16x32_bf16 v[4:7], v[164:167], v[240:243], 0
	v_mfma_f32_16x16x32_bf16 v[0:3], v[172:175], v[240:243], 0
	v_mfma_f32_16x16x32_bf16 v[52:55], v[168:171], v[220:223], v[52:55]
	v_mfma_f32_16x16x32_bf16 v[48:51], v[176:179], v[220:223], v[48:51]
	v_mfma_f32_16x16x32_bf16 v[36:39], v[168:171], v[228:231], v[36:39]
	v_mfma_f32_16x16x32_bf16 v[32:35], v[176:179], v[228:231], v[32:35]
	v_mfma_f32_16x16x32_bf16 v[20:23], v[168:171], v[236:239], v[20:23]
	v_mfma_f32_16x16x32_bf16 v[16:19], v[176:179], v[236:239], v[16:19]
	v_mfma_f32_16x16x32_bf16 v[4:7], v[168:171], v[244:247], v[4:7]
	v_mfma_f32_16x16x32_bf16 v[0:3], v[176:179], v[244:247], v[0:3]
	s_barrier
	s_setprio 0
	s_add_i32 s0, 0, 0x18000
	s_add_i32 s96, 0, 0x1c000
	v_add_u32_e32 v160, s0, v145
	v_add_u32_e32 v176, s96, v145
	ds_read_b128 v[140:143], v160
	ds_read_b128 v[152:155], v160 offset:1024
	ds_read_b128 v[156:159], v160 offset:2048
	ds_read_b128 v[160:163], v160 offset:3072
	ds_read_b128 v[164:167], v176
	ds_read_b128 v[168:171], v176 offset:1024
	ds_read_b128 v[172:175], v176 offset:2048
	ds_read_b128 v[176:179], v176 offset:3072
	s_add_u32 s88, s88, 0x40000
	s_addc_u32 s89, s89, 0
	s_mov_b32 m0, s26
	v_lshl_add_u64 v[252:253], s[88:89], 0, v[96:97]
	ds_read_b128 v[188:191], v151 offset:32768
	ds_read_b128 v[220:223], v151 offset:33792
	ds_read_b128 v[224:227], v151 offset:34816
	ds_read_b128 v[228:231], v151 offset:35840
	ds_read_b128 v[232:235], v151 offset:36864
	ds_read_b128 v[236:239], v151 offset:37888
	ds_read_b128 v[240:243], v151 offset:38912
	ds_read_b128 v[244:247], v151 offset:39936
	global_load_lds_dwordx4 v[252:253], off
	v_lshl_add_u64 v[252:253], s[88:89], 0, v[132:133]
	s_mov_b32 m0, s27
	s_nop 0
	global_load_lds_dwordx4 v[252:253], off
	s_waitcnt vmcnt(8)
	s_waitcnt lgkmcnt(0)
	s_setprio 1
	s_barrier
	v_mfma_f32_16x16x32_bf16 v[128:131], v[140:143], v[188:191], v[128:131]
	v_mfma_f32_16x16x32_bf16 v[124:127], v[156:159], v[188:191], v[124:127]
	v_mfma_f32_16x16x32_bf16 v[112:115], v[140:143], v[224:227], v[112:115]
	v_mfma_f32_16x16x32_bf16 v[108:111], v[156:159], v[224:227], v[108:111]
	v_mfma_f32_16x16x32_bf16 v[92:95], v[140:143], v[232:235], v[92:95]
	v_mfma_f32_16x16x32_bf16 v[88:91], v[156:159], v[232:235], v[88:91]
	v_mfma_f32_16x16x32_bf16 v[76:79], v[140:143], v[240:243], v[76:79]
	v_mfma_f32_16x16x32_bf16 v[72:75], v[156:159], v[240:243], v[72:75]
	v_mfma_f32_16x16x32_bf16 v[128:131], v[152:155], v[220:223], v[128:131]
	v_mfma_f32_16x16x32_bf16 v[124:127], v[160:163], v[220:223], v[124:127]
	v_mfma_f32_16x16x32_bf16 v[112:115], v[152:155], v[228:231], v[112:115]
	v_mfma_f32_16x16x32_bf16 v[108:111], v[160:163], v[228:231], v[108:111]
	v_mfma_f32_16x16x32_bf16 v[92:95], v[152:155], v[236:239], v[92:95]
	v_mfma_f32_16x16x32_bf16 v[88:91], v[160:163], v[236:239], v[88:91]
	v_mfma_f32_16x16x32_bf16 v[76:79], v[152:155], v[244:247], v[76:79]
	v_mfma_f32_16x16x32_bf16 v[72:75], v[160:163], v[244:247], v[72:75]
	v_mfma_f32_16x16x32_bf16 v[120:123], v[164:167], v[188:191], v[120:123]
	v_mfma_f32_16x16x32_bf16 v[116:119], v[172:175], v[188:191], v[116:119]
	v_mfma_f32_16x16x32_bf16 v[104:107], v[164:167], v[224:227], v[104:107]
	v_mfma_f32_16x16x32_bf16 v[100:103], v[172:175], v[224:227], v[100:103]
	v_mfma_f32_16x16x32_bf16 v[84:87], v[164:167], v[232:235], v[84:87]
	v_mfma_f32_16x16x32_bf16 v[80:83], v[172:175], v[232:235], v[80:83]
	v_mfma_f32_16x16x32_bf16 v[68:71], v[164:167], v[240:243], v[68:71]
	v_mfma_f32_16x16x32_bf16 v[64:67], v[172:175], v[240:243], v[64:67]
	v_mfma_f32_16x16x32_bf16 v[120:123], v[168:171], v[220:223], v[120:123]
	v_mfma_f32_16x16x32_bf16 v[116:119], v[176:179], v[220:223], v[116:119]
	v_mfma_f32_16x16x32_bf16 v[104:107], v[168:171], v[228:231], v[104:107]
	v_mfma_f32_16x16x32_bf16 v[100:103], v[176:179], v[228:231], v[100:103]
	v_mfma_f32_16x16x32_bf16 v[84:87], v[168:171], v[236:239], v[84:87]
	v_mfma_f32_16x16x32_bf16 v[80:83], v[176:179], v[236:239], v[80:83]
	v_mfma_f32_16x16x32_bf16 v[68:71], v[168:171], v[244:247], v[68:71]
	v_mfma_f32_16x16x32_bf16 v[64:67], v[176:179], v[244:247], v[64:67]
	s_barrier
	s_setprio 0
	s_add_i32 s0, s0, s1
	v_lshl_add_u64 v[180:181], v[180:181], 0, s[58:59]
	s_mov_b32 m0, s0
	ds_read_b128 v[188:191], v151 offset:49152
	ds_read_b128 v[220:223], v151 offset:50176
	ds_read_b128 v[224:227], v151 offset:51200
	ds_read_b128 v[228:231], v151 offset:52224
	ds_read_b128 v[232:235], v151 offset:53248
	ds_read_b128 v[236:239], v151 offset:54272
	ds_read_b128 v[240:243], v151 offset:55296
	ds_read_b128 v[244:247], v151 offset:56320
	global_load_lds_dwordx4 v[180:181], off
	s_add_i32 m0, s0, 0x2000
	s_add_u32 s86, s86, 0x40080
	v_lshl_add_u64 v[180:181], v[192:193], 0, s[58:59]
	s_addc_u32 s87, s87, 0
	s_add_i32 s0, s96, s1
	global_load_lds_dwordx4 v[180:181], off
	v_lshl_add_u64 v[180:181], s[86:87], 0, v[98:99]
	s_mov_b32 m0, s0
	s_nop 0
	global_load_lds_dwordx4 v[180:181], off
	v_lshl_add_u64 v[180:181], s[86:87], 0, v[134:135]
	s_add_i32 m0, s0, 0x2000
	s_nop 0
	global_load_lds_dwordx4 v[180:181], off
	v_lshl_add_u64 v[180:181], v[248:249], 0, s[58:59]
	s_mov_b32 m0, s42
	s_nop 0
	global_load_lds_dwordx4 v[180:181], off
	v_lshl_add_u64 v[180:181], v[250:251], 0, s[58:59]
	s_mov_b32 m0, s43
	s_nop 0
	global_load_lds_dwordx4 v[180:181], off
	s_waitcnt vmcnt(8)
	s_waitcnt lgkmcnt(0)
	s_setprio 1
	s_barrier
	v_mfma_f32_16x16x32_bf16 v[60:63], v[140:143], v[188:191], v[60:63]
	v_mfma_f32_16x16x32_bf16 v[56:59], v[156:159], v[188:191], v[56:59]
	v_mfma_f32_16x16x32_bf16 v[44:47], v[140:143], v[224:227], v[44:47]
	v_mfma_f32_16x16x32_bf16 v[40:43], v[156:159], v[224:227], v[40:43]
	v_mfma_f32_16x16x32_bf16 v[28:31], v[140:143], v[232:235], v[28:31]
	v_mfma_f32_16x16x32_bf16 v[24:27], v[156:159], v[232:235], v[24:27]
	v_mfma_f32_16x16x32_bf16 v[12:15], v[140:143], v[240:243], v[12:15]
	v_mfma_f32_16x16x32_bf16 v[8:11], v[156:159], v[240:243], v[8:11]
	v_mfma_f32_16x16x32_bf16 v[60:63], v[152:155], v[220:223], v[60:63]
	v_mfma_f32_16x16x32_bf16 v[56:59], v[160:163], v[220:223], v[56:59]
	v_mfma_f32_16x16x32_bf16 v[44:47], v[152:155], v[228:231], v[44:47]
	v_mfma_f32_16x16x32_bf16 v[40:43], v[160:163], v[228:231], v[40:43]
	v_mfma_f32_16x16x32_bf16 v[28:31], v[152:155], v[236:239], v[28:31]
	v_mfma_f32_16x16x32_bf16 v[24:27], v[160:163], v[236:239], v[24:27]
	v_mfma_f32_16x16x32_bf16 v[12:15], v[152:155], v[244:247], v[12:15]
	v_mfma_f32_16x16x32_bf16 v[8:11], v[160:163], v[244:247], v[8:11]
	v_mfma_f32_16x16x32_bf16 v[52:55], v[164:167], v[188:191], v[52:55]
	v_mfma_f32_16x16x32_bf16 v[48:51], v[172:175], v[188:191], v[48:51]
	v_mfma_f32_16x16x32_bf16 v[36:39], v[164:167], v[224:227], v[36:39]
	v_mfma_f32_16x16x32_bf16 v[32:35], v[172:175], v[224:227], v[32:35]
	v_mfma_f32_16x16x32_bf16 v[20:23], v[164:167], v[232:235], v[20:23]
	v_mfma_f32_16x16x32_bf16 v[16:19], v[172:175], v[232:235], v[16:19]
	v_mfma_f32_16x16x32_bf16 v[4:7], v[164:167], v[240:243], v[4:7]
	v_mfma_f32_16x16x32_bf16 v[0:3], v[172:175], v[240:243], v[0:3]
	v_mfma_f32_16x16x32_bf16 v[52:55], v[168:171], v[220:223], v[52:55]
	v_mfma_f32_16x16x32_bf16 v[48:51], v[176:179], v[220:223], v[48:51]
	v_mfma_f32_16x16x32_bf16 v[36:39], v[168:171], v[228:231], v[36:39]
	v_mfma_f32_16x16x32_bf16 v[32:35], v[176:179], v[228:231], v[32:35]
	v_mfma_f32_16x16x32_bf16 v[20:23], v[168:171], v[236:239], v[20:23]
	v_mfma_f32_16x16x32_bf16 v[16:19], v[176:179], v[236:239], v[16:19]
	v_mfma_f32_16x16x32_bf16 v[4:7], v[168:171], v[244:247], v[4:7]
	v_mfma_f32_16x16x32_bf16 v[0:3], v[176:179], v[244:247], v[0:3]
	s_barrier
	s_setprio 0
	s_add_i32 s90, s90, 2
	s_add_u32 s84, s84, 0x100
	s_addc_u32 s85, s85, 0
	s_add_u32 s75, s75, 0x100
	s_addc_u32 s77, s77, 0
	s_cmp_gt_u32 s90, 13
	s_cbranch_scc1 .Lpeel_exit_232
.LBB0_232:
	s_add_u32 s0, s84, 0xfffc0080
	s_addc_u32 s86, s85, -1
	s_add_i32 s96, 0, 0x10000
	s_cmp_eq_u32 s90, 12
	s_cselect_b32 s89, s66, s86
	s_cselect_b32 s88, s67, s0
	s_cselect_b32 s87, s68, s77
	s_cselect_b32 s86, s69, s75
	s_add_i32 s0, 0, 0x14000
	v_add_u32_e32 v160, s96, v145
	v_add_u32_e32 v176, s0, v145
	ds_read_b128 v[140:143], v160
	ds_read_b128 v[152:155], v160 offset:1024
	ds_read_b128 v[156:159], v160 offset:2048
	ds_read_b128 v[160:163], v160 offset:3072
	ds_read_b128 v[164:167], v176
	ds_read_b128 v[168:171], v176 offset:1024
	ds_read_b128 v[172:175], v176 offset:2048
	ds_read_b128 v[176:179], v176 offset:3072
	v_lshl_add_u64 v[180:181], s[84:85], 0, v[136:137]
	s_add_i32 m0, s22, 0xc000
	ds_read_b128 v[188:191], v151
	ds_read_b128 v[220:223], v151 offset:1024
	ds_read_b128 v[224:227], v151 offset:2048
	ds_read_b128 v[228:231], v151 offset:3072
	ds_read_b128 v[232:235], v151 offset:4096
	ds_read_b128 v[236:239], v151 offset:5120
	ds_read_b128 v[240:243], v151 offset:6144
	ds_read_b128 v[244:247], v151 offset:7168
	global_load_lds_dwordx4 v[180:181], off
	v_lshl_add_u64 v[180:181], s[84:85], 0, v[138:139]
	s_add_i32 m0, s22, 0xe000
	s_nop 0
	global_load_lds_dwordx4 v[180:181], off
	s_waitcnt vmcnt(8)
	s_waitcnt lgkmcnt(0)
	s_setprio 1
	s_barrier
	v_mfma_f32_16x16x32_bf16 v[128:131], v[140:143], v[188:191], v[128:131]
	v_mfma_f32_16x16x32_bf16 v[124:127], v[156:159], v[188:191], v[124:127]
	v_mfma_f32_16x16x32_bf16 v[112:115], v[140:143], v[224:227], v[112:115]
	v_mfma_f32_16x16x32_bf16 v[108:111], v[156:159], v[224:227], v[108:111]
	v_mfma_f32_16x16x32_bf16 v[92:95], v[140:143], v[232:235], v[92:95]
	v_mfma_f32_16x16x32_bf16 v[88:91], v[156:159], v[232:235], v[88:91]
	v_mfma_f32_16x16x32_bf16 v[76:79], v[140:143], v[240:243], v[76:79]
	v_mfma_f32_16x16x32_bf16 v[72:75], v[156:159], v[240:243], v[72:75]
	v_mfma_f32_16x16x32_bf16 v[128:131], v[152:155], v[220:223], v[128:131]
	v_mfma_f32_16x16x32_bf16 v[124:127], v[160:163], v[220:223], v[124:127]
	v_mfma_f32_16x16x32_bf16 v[112:115], v[152:155], v[228:231], v[112:115]
	v_mfma_f32_16x16x32_bf16 v[108:111], v[160:163], v[228:231], v[108:111]
	v_mfma_f32_16x16x32_bf16 v[92:95], v[152:155], v[236:239], v[92:95]
	v_mfma_f32_16x16x32_bf16 v[88:91], v[160:163], v[236:239], v[88:91]
	v_mfma_f32_16x16x32_bf16 v[76:79], v[152:155], v[244:247], v[76:79]
	v_mfma_f32_16x16x32_bf16 v[72:75], v[160:163], v[244:247], v[72:75]
	v_mfma_f32_16x16x32_bf16 v[120:123], v[164:167], v[188:191], v[120:123]
	v_mfma_f32_16x16x32_bf16 v[116:119], v[172:175], v[188:191], v[116:119]
	v_mfma_f32_16x16x32_bf16 v[104:107], v[164:167], v[224:227], v[104:107]
	v_mfma_f32_16x16x32_bf16 v[100:103], v[172:175], v[224:227], v[100:103]
	v_mfma_f32_16x16x32_bf16 v[84:87], v[164:167], v[232:235], v[84:87]
	v_mfma_f32_16x16x32_bf16 v[80:83], v[172:175], v[232:235], v[80:83]
	v_mfma_f32_16x16x32_bf16 v[68:71], v[164:167], v[240:243], v[68:71]
	v_mfma_f32_16x16x32_bf16 v[64:67], v[172:175], v[240:243], v[64:67]
	v_mfma_f32_16x16x32_bf16 v[120:123], v[168:171], v[220:223], v[120:123]
	v_mfma_f32_16x16x32_bf16 v[116:119], v[176:179], v[220:223], v[116:119]
	v_mfma_f32_16x16x32_bf16 v[104:107], v[168:171], v[228:231], v[104:107]
	v_mfma_f32_16x16x32_bf16 v[100:103], v[176:179], v[228:231], v[100:103]
	v_mfma_f32_16x16x32_bf16 v[84:87], v[168:171], v[236:239], v[84:87]
	v_mfma_f32_16x16x32_bf16 v[80:83], v[176:179], v[236:239], v[80:83]
	v_mfma_f32_16x16x32_bf16 v[68:71], v[168:171], v[244:247], v[68:71]
	v_mfma_f32_16x16x32_bf16 v[64:67], v[176:179], v[244:247], v[64:67]
	s_barrier
	s_setprio 0
	s_add_i32 s96, s96, s1
	v_lshl_add_u64 v[180:181], s[86:87], 0, v[98:99]
	s_mov_b32 m0, s96
	ds_read_b128 v[188:191], v151 offset:16384
	ds_read_b128 v[220:223], v151 offset:17408
	ds_read_b128 v[224:227], v151 offset:18432
	ds_read_b128 v[228:231], v151 offset:19456
	ds_read_b128 v[232:235], v151 offset:20480
	ds_read_b128 v[236:239], v151 offset:21504
	ds_read_b128 v[240:243], v151 offset:22528
	ds_read_b128 v[244:247], v151 offset:23552
	global_load_lds_dwordx4 v[180:181], off
	s_add_i32 m0, s96, 0x2000
	s_add_u32 s96, s86, 0x40000
	v_lshl_add_u64 v[192:193], s[86:87], 0, v[134:135]
	s_addc_u32 s97, s87, 0
	s_add_i32 s0, s0, s1
	global_load_lds_dwordx4 v[192:193], off
	v_lshl_add_u64 v[248:249], s[96:97], 0, v[98:99]
	s_mov_b32 m0, s0
	v_lshl_add_u64 v[250:251], s[88:89], 0, v[132:133]
	global_load_lds_dwordx4 v[248:249], off
	v_lshl_add_u64 v[248:249], s[96:97], 0, v[134:135]
	s_add_i32 m0, s0, 0x2000
	s_nop 0
	global_load_lds_dwordx4 v[248:249], off
	v_lshl_add_u64 v[248:249], s[88:89], 0, v[96:97]
	s_mov_b32 m0, s22
	s_nop 0
	global_load_lds_dwordx4 v[248:249], off
	s_mov_b32 m0, s23
	s_nop 0
	global_load_lds_dwordx4 v[250:251], off
	s_waitcnt vmcnt(8)
	s_waitcnt lgkmcnt(0)
	s_setprio 1
	s_barrier
	v_mfma_f32_16x16x32_bf16 v[60:63], v[140:143], v[188:191], v[60:63]
	v_mfma_f32_16x16x32_bf16 v[56:59], v[156:159], v[188:191], v[56:59]
	v_mfma_f32_16x16x32_bf16 v[44:47], v[140:143], v[224:227], v[44:47]
	v_mfma_f32_16x16x32_bf16 v[40:43], v[156:159], v[224:227], v[40:43]
	v_mfma_f32_16x16x32_bf16 v[28:31], v[140:143], v[232:235], v[28:31]
	v_mfma_f32_16x16x32_bf16 v[24:27], v[156:159], v[232:235], v[24:27]
	v_mfma_f32_16x16x32_bf16 v[12:15], v[140:143], v[240:243], v[12:15]
	v_mfma_f32_16x16x32_bf16 v[8:11], v[156:159], v[240:243], v[8:11]
	v_mfma_f32_16x16x32_bf16 v[60:63], v[152:155], v[220:223], v[60:63]
	v_mfma_f32_16x16x32_bf16 v[56:59], v[160:163], v[220:223], v[56:59]
	v_mfma_f32_16x16x32_bf16 v[44:47], v[152:155], v[228:231], v[44:47]
	v_mfma_f32_16x16x32_bf16 v[40:43], v[160:163], v[228:231], v[40:43]
	v_mfma_f32_16x16x32_bf16 v[28:31], v[152:155], v[236:239], v[28:31]
	v_mfma_f32_16x16x32_bf16 v[24:27], v[160:163], v[236:239], v[24:27]
	v_mfma_f32_16x16x32_bf16 v[12:15], v[152:155], v[244:247], v[12:15]
	v_mfma_f32_16x16x32_bf16 v[8:11], v[160:163], v[244:247], v[8:11]
	v_mfma_f32_16x16x32_bf16 v[52:55], v[164:167], v[188:191], v[52:55]
	v_mfma_f32_16x16x32_bf16 v[48:51], v[172:175], v[188:191], v[48:51]
	v_mfma_f32_16x16x32_bf16 v[36:39], v[164:167], v[224:227], v[36:39]
	v_mfma_f32_16x16x32_bf16 v[32:35], v[172:175], v[224:227], v[32:35]
	v_mfma_f32_16x16x32_bf16 v[20:23], v[164:167], v[232:235], v[20:23]
	v_mfma_f32_16x16x32_bf16 v[16:19], v[172:175], v[232:235], v[16:19]
	v_mfma_f32_16x16x32_bf16 v[4:7], v[164:167], v[240:243], v[4:7]
	v_mfma_f32_16x16x32_bf16 v[0:3], v[172:175], v[240:243], v[0:3]
	v_mfma_f32_16x16x32_bf16 v[52:55], v[168:171], v[220:223], v[52:55]
	v_mfma_f32_16x16x32_bf16 v[48:51], v[176:179], v[220:223], v[48:51]
	v_mfma_f32_16x16x32_bf16 v[36:39], v[168:171], v[228:231], v[36:39]
	v_mfma_f32_16x16x32_bf16 v[32:35], v[176:179], v[228:231], v[32:35]
	v_mfma_f32_16x16x32_bf16 v[20:23], v[168:171], v[236:239], v[20:23]
	v_mfma_f32_16x16x32_bf16 v[16:19], v[176:179], v[236:239], v[16:19]
	v_mfma_f32_16x16x32_bf16 v[4:7], v[168:171], v[244:247], v[4:7]
	v_mfma_f32_16x16x32_bf16 v[0:3], v[176:179], v[244:247], v[0:3]
	s_barrier
	s_setprio 0
	s_add_i32 s0, 0, 0x18000
	s_add_i32 s96, 0, 0x1c000
	v_add_u32_e32 v160, s0, v145
	v_add_u32_e32 v176, s96, v145
	ds_read_b128 v[140:143], v160
	ds_read_b128 v[152:155], v160 offset:1024
	ds_read_b128 v[156:159], v160 offset:2048
	ds_read_b128 v[160:163], v160 offset:3072
	ds_read_b128 v[164:167], v176
	ds_read_b128 v[168:171], v176 offset:1024
	ds_read_b128 v[172:175], v176 offset:2048
	ds_read_b128 v[176:179], v176 offset:3072
	s_add_u32 s88, s88, 0x40000
	s_addc_u32 s89, s89, 0
	s_mov_b32 m0, s26
	v_lshl_add_u64 v[252:253], s[88:89], 0, v[96:97]
	ds_read_b128 v[188:191], v151 offset:32768
	ds_read_b128 v[220:223], v151 offset:33792
	ds_read_b128 v[224:227], v151 offset:34816
	ds_read_b128 v[228:231], v151 offset:35840
	ds_read_b128 v[232:235], v151 offset:36864
	ds_read_b128 v[236:239], v151 offset:37888
	ds_read_b128 v[240:243], v151 offset:38912
	ds_read_b128 v[244:247], v151 offset:39936
	global_load_lds_dwordx4 v[252:253], off
	v_lshl_add_u64 v[252:253], s[88:89], 0, v[132:133]
	s_mov_b32 m0, s27
	s_nop 0
	global_load_lds_dwordx4 v[252:253], off
	s_waitcnt vmcnt(8)
	s_waitcnt lgkmcnt(0)
	s_setprio 1
	s_barrier
	v_mfma_f32_16x16x32_bf16 v[128:131], v[140:143], v[188:191], v[128:131]
	v_mfma_f32_16x16x32_bf16 v[124:127], v[156:159], v[188:191], v[124:127]
	v_mfma_f32_16x16x32_bf16 v[112:115], v[140:143], v[224:227], v[112:115]
	v_mfma_f32_16x16x32_bf16 v[108:111], v[156:159], v[224:227], v[108:111]
	v_mfma_f32_16x16x32_bf16 v[92:95], v[140:143], v[232:235], v[92:95]
	v_mfma_f32_16x16x32_bf16 v[88:91], v[156:159], v[232:235], v[88:91]
	v_mfma_f32_16x16x32_bf16 v[76:79], v[140:143], v[240:243], v[76:79]
	v_mfma_f32_16x16x32_bf16 v[72:75], v[156:159], v[240:243], v[72:75]
	v_mfma_f32_16x16x32_bf16 v[128:131], v[152:155], v[220:223], v[128:131]
	v_mfma_f32_16x16x32_bf16 v[124:127], v[160:163], v[220:223], v[124:127]
	v_mfma_f32_16x16x32_bf16 v[112:115], v[152:155], v[228:231], v[112:115]
	v_mfma_f32_16x16x32_bf16 v[108:111], v[160:163], v[228:231], v[108:111]
	v_mfma_f32_16x16x32_bf16 v[92:95], v[152:155], v[236:239], v[92:95]
	v_mfma_f32_16x16x32_bf16 v[88:91], v[160:163], v[236:239], v[88:91]
	v_mfma_f32_16x16x32_bf16 v[76:79], v[152:155], v[244:247], v[76:79]
	v_mfma_f32_16x16x32_bf16 v[72:75], v[160:163], v[244:247], v[72:75]
	v_mfma_f32_16x16x32_bf16 v[120:123], v[164:167], v[188:191], v[120:123]
	v_mfma_f32_16x16x32_bf16 v[116:119], v[172:175], v[188:191], v[116:119]
	v_mfma_f32_16x16x32_bf16 v[104:107], v[164:167], v[224:227], v[104:107]
	v_mfma_f32_16x16x32_bf16 v[100:103], v[172:175], v[224:227], v[100:103]
	v_mfma_f32_16x16x32_bf16 v[84:87], v[164:167], v[232:235], v[84:87]
	v_mfma_f32_16x16x32_bf16 v[80:83], v[172:175], v[232:235], v[80:83]
	v_mfma_f32_16x16x32_bf16 v[68:71], v[164:167], v[240:243], v[68:71]
	v_mfma_f32_16x16x32_bf16 v[64:67], v[172:175], v[240:243], v[64:67]
	v_mfma_f32_16x16x32_bf16 v[120:123], v[168:171], v[220:223], v[120:123]
	v_mfma_f32_16x16x32_bf16 v[116:119], v[176:179], v[220:223], v[116:119]
	v_mfma_f32_16x16x32_bf16 v[104:107], v[168:171], v[228:231], v[104:107]
	v_mfma_f32_16x16x32_bf16 v[100:103], v[176:179], v[228:231], v[100:103]
	v_mfma_f32_16x16x32_bf16 v[84:87], v[168:171], v[236:239], v[84:87]
	v_mfma_f32_16x16x32_bf16 v[80:83], v[176:179], v[236:239], v[80:83]
	v_mfma_f32_16x16x32_bf16 v[68:71], v[168:171], v[244:247], v[68:71]
	v_mfma_f32_16x16x32_bf16 v[64:67], v[176:179], v[244:247], v[64:67]
	s_barrier
	s_setprio 0
	s_add_i32 s0, s0, s1
	v_lshl_add_u64 v[180:181], v[180:181], 0, s[58:59]
	s_mov_b32 m0, s0
	ds_read_b128 v[188:191], v151 offset:49152
	ds_read_b128 v[220:223], v151 offset:50176
	ds_read_b128 v[224:227], v151 offset:51200
	ds_read_b128 v[228:231], v151 offset:52224
	ds_read_b128 v[232:235], v151 offset:53248
	ds_read_b128 v[236:239], v151 offset:54272
	ds_read_b128 v[240:243], v151 offset:55296
	ds_read_b128 v[244:247], v151 offset:56320
	global_load_lds_dwordx4 v[180:181], off
	s_add_i32 m0, s0, 0x2000
	s_add_u32 s86, s86, 0x40080
	v_lshl_add_u64 v[180:181], v[192:193], 0, s[58:59]
	s_addc_u32 s87, s87, 0
	s_add_i32 s0, s96, s1
	global_load_lds_dwordx4 v[180:181], off
	v_lshl_add_u64 v[180:181], s[86:87], 0, v[98:99]
	s_mov_b32 m0, s0
	s_nop 0
	global_load_lds_dwordx4 v[180:181], off
	v_lshl_add_u64 v[180:181], s[86:87], 0, v[134:135]
	s_add_i32 m0, s0, 0x2000
	s_nop 0
	global_load_lds_dwordx4 v[180:181], off
	v_lshl_add_u64 v[180:181], v[248:249], 0, s[58:59]
	s_mov_b32 m0, s42
	s_nop 0
	global_load_lds_dwordx4 v[180:181], off
	v_lshl_add_u64 v[180:181], v[250:251], 0, s[58:59]
	s_mov_b32 m0, s43
	s_nop 0
	global_load_lds_dwordx4 v[180:181], off
	s_waitcnt vmcnt(8)
	s_waitcnt lgkmcnt(0)
	s_setprio 1
	s_barrier
	v_mfma_f32_16x16x32_bf16 v[60:63], v[140:143], v[188:191], v[60:63]
	v_mfma_f32_16x16x32_bf16 v[56:59], v[156:159], v[188:191], v[56:59]
	v_mfma_f32_16x16x32_bf16 v[44:47], v[140:143], v[224:227], v[44:47]
	v_mfma_f32_16x16x32_bf16 v[40:43], v[156:159], v[224:227], v[40:43]
	v_mfma_f32_16x16x32_bf16 v[28:31], v[140:143], v[232:235], v[28:31]
	v_mfma_f32_16x16x32_bf16 v[24:27], v[156:159], v[232:235], v[24:27]
	v_mfma_f32_16x16x32_bf16 v[12:15], v[140:143], v[240:243], v[12:15]
	v_mfma_f32_16x16x32_bf16 v[8:11], v[156:159], v[240:243], v[8:11]
	v_mfma_f32_16x16x32_bf16 v[60:63], v[152:155], v[220:223], v[60:63]
	v_mfma_f32_16x16x32_bf16 v[56:59], v[160:163], v[220:223], v[56:59]
	v_mfma_f32_16x16x32_bf16 v[44:47], v[152:155], v[228:231], v[44:47]
	v_mfma_f32_16x16x32_bf16 v[40:43], v[160:163], v[228:231], v[40:43]
	v_mfma_f32_16x16x32_bf16 v[28:31], v[152:155], v[236:239], v[28:31]
	v_mfma_f32_16x16x32_bf16 v[24:27], v[160:163], v[236:239], v[24:27]
	v_mfma_f32_16x16x32_bf16 v[12:15], v[152:155], v[244:247], v[12:15]
	v_mfma_f32_16x16x32_bf16 v[8:11], v[160:163], v[244:247], v[8:11]
	v_mfma_f32_16x16x32_bf16 v[52:55], v[164:167], v[188:191], v[52:55]
	v_mfma_f32_16x16x32_bf16 v[48:51], v[172:175], v[188:191], v[48:51]
	v_mfma_f32_16x16x32_bf16 v[36:39], v[164:167], v[224:227], v[36:39]
	v_mfma_f32_16x16x32_bf16 v[32:35], v[172:175], v[224:227], v[32:35]
	v_mfma_f32_16x16x32_bf16 v[20:23], v[164:167], v[232:235], v[20:23]
	v_mfma_f32_16x16x32_bf16 v[16:19], v[172:175], v[232:235], v[16:19]
	v_mfma_f32_16x16x32_bf16 v[4:7], v[164:167], v[240:243], v[4:7]
	v_mfma_f32_16x16x32_bf16 v[0:3], v[172:175], v[240:243], v[0:3]
	v_mfma_f32_16x16x32_bf16 v[52:55], v[168:171], v[220:223], v[52:55]
	v_mfma_f32_16x16x32_bf16 v[48:51], v[176:179], v[220:223], v[48:51]
	v_mfma_f32_16x16x32_bf16 v[36:39], v[168:171], v[228:231], v[36:39]
	v_mfma_f32_16x16x32_bf16 v[32:35], v[176:179], v[228:231], v[32:35]
	v_mfma_f32_16x16x32_bf16 v[20:23], v[168:171], v[236:239], v[20:23]
	v_mfma_f32_16x16x32_bf16 v[16:19], v[176:179], v[236:239], v[16:19]
	v_mfma_f32_16x16x32_bf16 v[4:7], v[168:171], v[244:247], v[4:7]
	v_mfma_f32_16x16x32_bf16 v[0:3], v[176:179], v[244:247], v[0:3]
	s_barrier
	s_setprio 0
	s_add_i32 s90, s90, 2
	s_add_u32 s84, s84, 0x100
	s_addc_u32 s85, s85, 0
	s_add_u32 s75, s75, 0x100
	s_addc_u32 s77, s77, 0
	s_cmp_gt_u32 s90, 13
	s_cbranch_scc0 .LBB0_232

.LBB0_309:
	s_add_u32 s84, s84, 0x80
	s_addc_u32 s85, s85, 0
	s_add_u32 s26, s86, 0x100
	s_addc_u32 s27, s87, 0
	s_mov_b32 s0, 0
	s_waitcnt lgkmcnt(0)
	s_waitcnt vmcnt(0)
	s_add_i32 s42, s0, 2
	s_add_u32 s66, s84, 0x80
	s_addc_u32 s86, s85, 0
	s_add_i32 s97, 0, 0x10000
	s_cmp_eq_u32 s88, s0
	s_cselect_b32 s87, s81, s86
	s_cselect_b32 s86, s80, s66
	s_cselect_b32 vcc_hi, s83, s27
	s_cselect_b32 vcc_lo, s82, s26
	s_add_i32 s0, 0, 0x14000
	v_add_u32_e32 v152, s97, v161
	v_add_u32_e32 v172, s0, v161
	ds_read_b128 v[132:135], v152
	ds_read_b128 v[136:139], v152 offset:1024
	ds_read_b128 v[148:151], v152 offset:2048
	ds_read_b128 v[152:155], v152 offset:3072
	ds_read_b128 v[156:159], v172
	ds_read_b128 v[164:167], v172 offset:1024
	ds_read_b128 v[168:171], v172 offset:2048
	ds_read_b128 v[172:175], v172 offset:3072
	v_lshl_add_u64 v[180:181], s[84:85], 0, v[144:145]
	s_add_i32 m0, s23, 0xc000
	ds_read_b128 v[176:179], v163
	ds_read_b128 v[188:191], v163 offset:1024
	ds_read_b128 v[220:223], v163 offset:2048
	ds_read_b128 v[224:227], v163 offset:3072
	ds_read_b128 v[228:231], v163 offset:4096
	ds_read_b128 v[232:235], v163 offset:5120
	ds_read_b128 v[236:239], v163 offset:6144
	ds_read_b128 v[240:243], v163 offset:7168
	global_load_lds_dwordx4 v[180:181], off
	v_lshl_add_u64 v[180:181], s[84:85], 0, v[146:147]
	s_add_i32 m0, s23, 0xe000
	s_nop 0
	global_load_lds_dwordx4 v[180:181], off
	s_waitcnt vmcnt(8)
	s_waitcnt lgkmcnt(0)
	s_setprio 1
	s_barrier
	v_mfma_f32_16x16x32_bf16 v[128:131], v[132:135], v[176:179], 0
	v_mfma_f32_16x16x32_bf16 v[124:127], v[148:151], v[176:179], 0
	v_mfma_f32_16x16x32_bf16 v[112:115], v[132:135], v[220:223], 0
	v_mfma_f32_16x16x32_bf16 v[108:111], v[148:151], v[220:223], 0
	v_mfma_f32_16x16x32_bf16 v[92:95], v[132:135], v[228:231], 0
	v_mfma_f32_16x16x32_bf16 v[88:91], v[148:151], v[228:231], 0
	v_mfma_f32_16x16x32_bf16 v[76:79], v[132:135], v[236:239], 0
	v_mfma_f32_16x16x32_bf16 v[72:75], v[148:151], v[236:239], 0
	v_mfma_f32_16x16x32_bf16 v[128:131], v[136:139], v[188:191], v[128:131]
	v_mfma_f32_16x16x32_bf16 v[124:127], v[152:155], v[188:191], v[124:127]
	v_mfma_f32_16x16x32_bf16 v[112:115], v[136:139], v[224:227], v[112:115]
	v_mfma_f32_16x16x32_bf16 v[108:111], v[152:155], v[224:227], v[108:111]
	v_mfma_f32_16x16x32_bf16 v[92:95], v[136:139], v[232:235], v[92:95]
	v_mfma_f32_16x16x32_bf16 v[88:91], v[152:155], v[232:235], v[88:91]
	v_mfma_f32_16x16x32_bf16 v[76:79], v[136:139], v[240:243], v[76:79]
	v_mfma_f32_16x16x32_bf16 v[72:75], v[152:155], v[240:243], v[72:75]
	v_mfma_f32_16x16x32_bf16 v[120:123], v[156:159], v[176:179], 0
	v_mfma_f32_16x16x32_bf16 v[116:119], v[168:171], v[176:179], 0
	v_mfma_f32_16x16x32_bf16 v[104:107], v[156:159], v[220:223], 0
	v_mfma_f32_16x16x32_bf16 v[100:103], v[168:171], v[220:223], 0
	v_mfma_f32_16x16x32_bf16 v[84:87], v[156:159], v[228:231], 0
	v_mfma_f32_16x16x32_bf16 v[80:83], v[168:171], v[228:231], 0
	v_mfma_f32_16x16x32_bf16 v[68:71], v[156:159], v[236:239], 0
	v_mfma_f32_16x16x32_bf16 v[64:67], v[168:171], v[236:239], 0
	v_mfma_f32_16x16x32_bf16 v[120:123], v[164:167], v[188:191], v[120:123]
	v_mfma_f32_16x16x32_bf16 v[116:119], v[172:175], v[188:191], v[116:119]
	v_mfma_f32_16x16x32_bf16 v[104:107], v[164:167], v[224:227], v[104:107]
	v_mfma_f32_16x16x32_bf16 v[100:103], v[172:175], v[224:227], v[100:103]
	v_mfma_f32_16x16x32_bf16 v[84:87], v[164:167], v[232:235], v[84:87]
	v_mfma_f32_16x16x32_bf16 v[80:83], v[172:175], v[232:235], v[80:83]
	v_mfma_f32_16x16x32_bf16 v[68:71], v[164:167], v[240:243], v[68:71]
	v_mfma_f32_16x16x32_bf16 v[64:67], v[172:175], v[240:243], v[64:67]
	s_barrier
	s_setprio 0
	s_add_i32 s66, s97, s10
	v_lshl_add_u64 v[180:181], vcc, 0, v[98:99]
	s_mov_b32 m0, s66
	ds_read_b128 v[176:179], v163 offset:16384
	ds_read_b128 v[188:191], v163 offset:17408
	ds_read_b128 v[220:223], v163 offset:18432
	ds_read_b128 v[224:227], v163 offset:19456
	ds_read_b128 v[228:231], v163 offset:20480
	ds_read_b128 v[232:235], v163 offset:21504
	ds_read_b128 v[236:239], v163 offset:22528
	ds_read_b128 v[240:243], v163 offset:23552
	global_load_lds_dwordx4 v[180:181], off
	s_add_i32 m0, s66, 0x2000
	v_lshl_add_u64 v[192:193], vcc, 0, v[142:143]
	s_add_u32 vcc_lo, vcc_lo, s72
	s_addc_u32 vcc_hi, vcc_hi, 0
	s_add_i32 s0, s0, s10
	global_load_lds_dwordx4 v[192:193], off
	v_lshl_add_u64 v[244:245], vcc, 0, v[98:99]
	s_mov_b32 m0, s0
	v_lshl_add_u64 v[246:247], vcc, 0, v[142:143]
	global_load_lds_dwordx4 v[244:245], off
	s_add_i32 m0, s0, 0x2000
	v_lshl_add_u64 v[248:249], s[86:87], 0, v[96:97]
	global_load_lds_dwordx4 v[246:247], off
	s_mov_b32 m0, s23
	v_lshl_add_u64 v[250:251], s[86:87], 0, v[140:141]
	global_load_lds_dwordx4 v[248:249], off
	s_mov_b32 m0, s33
	s_nop 0
	global_load_lds_dwordx4 v[250:251], off
	s_waitcnt vmcnt(8)
	s_waitcnt lgkmcnt(0)
	s_setprio 1
	s_barrier
	v_mfma_f32_16x16x32_bf16 v[60:63], v[132:135], v[176:179], 0
	v_mfma_f32_16x16x32_bf16 v[56:59], v[148:151], v[176:179], 0
	v_mfma_f32_16x16x32_bf16 v[44:47], v[132:135], v[220:223], 0
	v_mfma_f32_16x16x32_bf16 v[40:43], v[148:151], v[220:223], 0
	v_mfma_f32_16x16x32_bf16 v[28:31], v[132:135], v[228:231], 0
	v_mfma_f32_16x16x32_bf16 v[24:27], v[148:151], v[228:231], 0
	v_mfma_f32_16x16x32_bf16 v[12:15], v[132:135], v[236:239], 0
	v_mfma_f32_16x16x32_bf16 v[8:11], v[148:151], v[236:239], 0
	v_mfma_f32_16x16x32_bf16 v[60:63], v[136:139], v[188:191], v[60:63]
	v_mfma_f32_16x16x32_bf16 v[56:59], v[152:155], v[188:191], v[56:59]
	v_mfma_f32_16x16x32_bf16 v[44:47], v[136:139], v[224:227], v[44:47]
	v_mfma_f32_16x16x32_bf16 v[40:43], v[152:155], v[224:227], v[40:43]
	v_mfma_f32_16x16x32_bf16 v[28:31], v[136:139], v[232:235], v[28:31]
	v_mfma_f32_16x16x32_bf16 v[24:27], v[152:155], v[232:235], v[24:27]
	v_mfma_f32_16x16x32_bf16 v[12:15], v[136:139], v[240:243], v[12:15]
	v_mfma_f32_16x16x32_bf16 v[8:11], v[152:155], v[240:243], v[8:11]
	v_mfma_f32_16x16x32_bf16 v[52:55], v[156:159], v[176:179], 0
	v_mfma_f32_16x16x32_bf16 v[48:51], v[168:171], v[176:179], 0
	v_mfma_f32_16x16x32_bf16 v[36:39], v[156:159], v[220:223], 0
	v_mfma_f32_16x16x32_bf16 v[32:35], v[168:171], v[220:223], 0
	v_mfma_f32_16x16x32_bf16 v[20:23], v[156:159], v[228:231], 0
	v_mfma_f32_16x16x32_bf16 v[16:19], v[168:171], v[228:231], 0
	v_mfma_f32_16x16x32_bf16 v[4:7], v[156:159], v[236:239], 0
	v_mfma_f32_16x16x32_bf16 v[0:3], v[168:171], v[236:239], 0
	v_mfma_f32_16x16x32_bf16 v[52:55], v[164:167], v[188:191], v[52:55]
	v_mfma_f32_16x16x32_bf16 v[48:51], v[172:175], v[188:191], v[48:51]
	v_mfma_f32_16x16x32_bf16 v[36:39], v[164:167], v[224:227], v[36:39]
	v_mfma_f32_16x16x32_bf16 v[32:35], v[172:175], v[224:227], v[32:35]
	v_mfma_f32_16x16x32_bf16 v[20:23], v[164:167], v[232:235], v[20:23]
	v_mfma_f32_16x16x32_bf16 v[16:19], v[172:175], v[232:235], v[16:19]
	v_mfma_f32_16x16x32_bf16 v[4:7], v[164:167], v[240:243], v[4:7]
	v_mfma_f32_16x16x32_bf16 v[0:3], v[172:175], v[240:243], v[0:3]
	s_barrier
	s_setprio 0
	s_add_i32 s0, 0, 0x18000
	s_add_i32 s66, 0, 0x1c000
	v_add_u32_e32 v152, s0, v161
	v_add_u32_e32 v172, s66, v161
	ds_read_b128 v[132:135], v152
	ds_read_b128 v[136:139], v152 offset:1024
	ds_read_b128 v[148:151], v152 offset:2048
	ds_read_b128 v[152:155], v152 offset:3072
	ds_read_b128 v[156:159], v172
	ds_read_b128 v[164:167], v172 offset:1024
	ds_read_b128 v[168:171], v172 offset:2048
	ds_read_b128 v[172:175], v172 offset:3072
	s_add_u32 s86, s86, s72
	s_addc_u32 s87, s87, 0
	s_mov_b32 m0, s43
	v_lshl_add_u64 v[252:253], s[86:87], 0, v[96:97]
	ds_read_b128 v[176:179], v163 offset:32768
	ds_read_b128 v[188:191], v163 offset:33792
	ds_read_b128 v[220:223], v163 offset:34816
	ds_read_b128 v[224:227], v163 offset:35840
	ds_read_b128 v[228:231], v163 offset:36864
	ds_read_b128 v[232:235], v163 offset:37888
	ds_read_b128 v[236:239], v163 offset:38912
	ds_read_b128 v[240:243], v163 offset:39936
	global_load_lds_dwordx4 v[252:253], off
	v_lshl_add_u64 v[252:253], s[86:87], 0, v[140:141]
	s_mov_b32 m0, s44
	s_nop 0
	global_load_lds_dwordx4 v[252:253], off
	s_waitcnt vmcnt(8)
	s_waitcnt lgkmcnt(0)
	s_setprio 1
	s_barrier
	v_mfma_f32_16x16x32_bf16 v[128:131], v[132:135], v[176:179], v[128:131]
	v_mfma_f32_16x16x32_bf16 v[124:127], v[148:151], v[176:179], v[124:127]
	v_mfma_f32_16x16x32_bf16 v[112:115], v[132:135], v[220:223], v[112:115]
	v_mfma_f32_16x16x32_bf16 v[108:111], v[148:151], v[220:223], v[108:111]
	v_mfma_f32_16x16x32_bf16 v[92:95], v[132:135], v[228:231], v[92:95]
	v_mfma_f32_16x16x32_bf16 v[88:91], v[148:151], v[228:231], v[88:91]
	v_mfma_f32_16x16x32_bf16 v[76:79], v[132:135], v[236:239], v[76:79]
	v_mfma_f32_16x16x32_bf16 v[72:75], v[148:151], v[236:239], v[72:75]
	v_mfma_f32_16x16x32_bf16 v[128:131], v[136:139], v[188:191], v[128:131]
	v_mfma_f32_16x16x32_bf16 v[124:127], v[152:155], v[188:191], v[124:127]
	v_mfma_f32_16x16x32_bf16 v[112:115], v[136:139], v[224:227], v[112:115]
	v_mfma_f32_16x16x32_bf16 v[108:111], v[152:155], v[224:227], v[108:111]
	v_mfma_f32_16x16x32_bf16 v[92:95], v[136:139], v[232:235], v[92:95]
	v_mfma_f32_16x16x32_bf16 v[88:91], v[152:155], v[232:235], v[88:91]
	v_mfma_f32_16x16x32_bf16 v[76:79], v[136:139], v[240:243], v[76:79]
	v_mfma_f32_16x16x32_bf16 v[72:75], v[152:155], v[240:243], v[72:75]
	v_mfma_f32_16x16x32_bf16 v[120:123], v[156:159], v[176:179], v[120:123]
	v_mfma_f32_16x16x32_bf16 v[116:119], v[168:171], v[176:179], v[116:119]
	v_mfma_f32_16x16x32_bf16 v[104:107], v[156:159], v[220:223], v[104:107]
	v_mfma_f32_16x16x32_bf16 v[100:103], v[168:171], v[220:223], v[100:103]
	v_mfma_f32_16x16x32_bf16 v[84:87], v[156:159], v[228:231], v[84:87]
	v_mfma_f32_16x16x32_bf16 v[80:83], v[168:171], v[228:231], v[80:83]
	v_mfma_f32_16x16x32_bf16 v[68:71], v[156:159], v[236:239], v[68:71]
	v_mfma_f32_16x16x32_bf16 v[64:67], v[168:171], v[236:239], v[64:67]
	v_mfma_f32_16x16x32_bf16 v[120:123], v[164:167], v[188:191], v[120:123]
	v_mfma_f32_16x16x32_bf16 v[116:119], v[172:175], v[188:191], v[116:119]
	v_mfma_f32_16x16x32_bf16 v[104:107], v[164:167], v[224:227], v[104:107]
	v_mfma_f32_16x16x32_bf16 v[100:103], v[172:175], v[224:227], v[100:103]
	v_mfma_f32_16x16x32_bf16 v[84:87], v[164:167], v[232:235], v[84:87]
	v_mfma_f32_16x16x32_bf16 v[80:83], v[172:175], v[232:235], v[80:83]
	v_mfma_f32_16x16x32_bf16 v[68:71], v[164:167], v[240:243], v[68:71]
	v_mfma_f32_16x16x32_bf16 v[64:67], v[172:175], v[240:243], v[64:67]
	s_barrier
	s_setprio 0
	s_add_i32 s0, s0, s10
	v_lshl_add_u64 v[180:181], v[180:181], 0, s[58:59]
	s_mov_b32 m0, s0
	ds_read_b128 v[176:179], v163 offset:49152
	ds_read_b128 v[188:191], v163 offset:50176
	ds_read_b128 v[220:223], v163 offset:51200
	ds_read_b128 v[224:227], v163 offset:52224
	ds_read_b128 v[228:231], v163 offset:53248
	ds_read_b128 v[232:235], v163 offset:54272
	ds_read_b128 v[236:239], v163 offset:55296
	ds_read_b128 v[240:243], v163 offset:56320
	global_load_lds_dwordx4 v[180:181], off
	v_lshl_add_u64 v[180:181], v[192:193], 0, s[58:59]
	s_add_i32 m0, s0, 0x2000
	s_add_i32 s0, s66, s10
	global_load_lds_dwordx4 v[180:181], off
	v_lshl_add_u64 v[180:181], v[244:245], 0, s[58:59]
	s_mov_b32 m0, s0
	s_nop 0
	global_load_lds_dwordx4 v[180:181], off
	v_lshl_add_u64 v[180:181], v[246:247], 0, s[58:59]
	s_add_i32 m0, s0, 0x2000
	s_nop 0
	global_load_lds_dwordx4 v[180:181], off
	v_lshl_add_u64 v[180:181], v[248:249], 0, s[58:59]
	s_mov_b32 m0, s47
	s_nop 0
	global_load_lds_dwordx4 v[180:181], off
	v_lshl_add_u64 v[180:181], v[250:251], 0, s[58:59]
	s_mov_b32 m0, s56
	s_nop 0
	global_load_lds_dwordx4 v[180:181], off
	s_waitcnt vmcnt(8)
	s_waitcnt lgkmcnt(0)
	s_setprio 1
	s_barrier
	v_mfma_f32_16x16x32_bf16 v[60:63], v[132:135], v[176:179], v[60:63]
	v_mfma_f32_16x16x32_bf16 v[56:59], v[148:151], v[176:179], v[56:59]
	v_mfma_f32_16x16x32_bf16 v[44:47], v[132:135], v[220:223], v[44:47]
	v_mfma_f32_16x16x32_bf16 v[40:43], v[148:151], v[220:223], v[40:43]
	v_mfma_f32_16x16x32_bf16 v[28:31], v[132:135], v[228:231], v[28:31]
	v_mfma_f32_16x16x32_bf16 v[24:27], v[148:151], v[228:231], v[24:27]
	v_mfma_f32_16x16x32_bf16 v[12:15], v[132:135], v[236:239], v[12:15]
	v_mfma_f32_16x16x32_bf16 v[8:11], v[148:151], v[236:239], v[8:11]
	v_mfma_f32_16x16x32_bf16 v[60:63], v[136:139], v[188:191], v[60:63]
	v_mfma_f32_16x16x32_bf16 v[56:59], v[152:155], v[188:191], v[56:59]
	v_mfma_f32_16x16x32_bf16 v[44:47], v[136:139], v[224:227], v[44:47]
	v_mfma_f32_16x16x32_bf16 v[40:43], v[152:155], v[224:227], v[40:43]
	v_mfma_f32_16x16x32_bf16 v[28:31], v[136:139], v[232:235], v[28:31]
	v_mfma_f32_16x16x32_bf16 v[24:27], v[152:155], v[232:235], v[24:27]
	v_mfma_f32_16x16x32_bf16 v[12:15], v[136:139], v[240:243], v[12:15]
	v_mfma_f32_16x16x32_bf16 v[8:11], v[152:155], v[240:243], v[8:11]
	v_mfma_f32_16x16x32_bf16 v[52:55], v[156:159], v[176:179], v[52:55]
	v_mfma_f32_16x16x32_bf16 v[48:51], v[168:171], v[176:179], v[48:51]
	v_mfma_f32_16x16x32_bf16 v[36:39], v[156:159], v[220:223], v[36:39]
	v_mfma_f32_16x16x32_bf16 v[32:35], v[168:171], v[220:223], v[32:35]
	v_mfma_f32_16x16x32_bf16 v[20:23], v[156:159], v[228:231], v[20:23]
	v_mfma_f32_16x16x32_bf16 v[16:19], v[168:171], v[228:231], v[16:19]
	v_mfma_f32_16x16x32_bf16 v[4:7], v[156:159], v[236:239], v[4:7]
	v_mfma_f32_16x16x32_bf16 v[0:3], v[168:171], v[236:239], v[0:3]
	v_mfma_f32_16x16x32_bf16 v[52:55], v[164:167], v[188:191], v[52:55]
	v_mfma_f32_16x16x32_bf16 v[48:51], v[172:175], v[188:191], v[48:51]
	v_mfma_f32_16x16x32_bf16 v[36:39], v[164:167], v[224:227], v[36:39]
	v_mfma_f32_16x16x32_bf16 v[32:35], v[172:175], v[224:227], v[32:35]
	v_mfma_f32_16x16x32_bf16 v[20:23], v[164:167], v[232:235], v[20:23]
	v_mfma_f32_16x16x32_bf16 v[16:19], v[172:175], v[232:235], v[16:19]
	v_mfma_f32_16x16x32_bf16 v[4:7], v[164:167], v[240:243], v[4:7]
	v_mfma_f32_16x16x32_bf16 v[0:3], v[172:175], v[240:243], v[0:3]
	s_barrier
	s_setprio 0
	s_add_u32 s84, s84, 0x100
	s_addc_u32 s85, s85, 0
	s_add_u32 s26, s26, 0x100
	s_addc_u32 s27, s27, 0
	s_cmp_ge_u32 s42, s67
	s_mov_b32 s0, s42
	s_cbranch_scc1 .Lpeel_exit_310
.LBB0_310:
	s_add_i32 s42, s0, 2
	s_add_u32 s66, s84, 0x80
	s_addc_u32 s86, s85, 0
	s_add_i32 s97, 0, 0x10000
	s_cmp_eq_u32 s88, s0
	s_cselect_b32 s87, s81, s86
	s_cselect_b32 s86, s80, s66
	s_cselect_b32 vcc_hi, s83, s27
	s_cselect_b32 vcc_lo, s82, s26
	s_add_i32 s0, 0, 0x14000
	v_add_u32_e32 v152, s97, v161
	v_add_u32_e32 v172, s0, v161
	ds_read_b128 v[132:135], v152
	ds_read_b128 v[136:139], v152 offset:1024
	ds_read_b128 v[148:151], v152 offset:2048
	ds_read_b128 v[152:155], v152 offset:3072
	ds_read_b128 v[156:159], v172
	ds_read_b128 v[164:167], v172 offset:1024
	ds_read_b128 v[168:171], v172 offset:2048
	ds_read_b128 v[172:175], v172 offset:3072
	v_lshl_add_u64 v[180:181], s[84:85], 0, v[144:145]
	s_add_i32 m0, s23, 0xc000
	ds_read_b128 v[176:179], v163
	ds_read_b128 v[188:191], v163 offset:1024
	ds_read_b128 v[220:223], v163 offset:2048
	ds_read_b128 v[224:227], v163 offset:3072
	ds_read_b128 v[228:231], v163 offset:4096
	ds_read_b128 v[232:235], v163 offset:5120
	ds_read_b128 v[236:239], v163 offset:6144
	ds_read_b128 v[240:243], v163 offset:7168
	global_load_lds_dwordx4 v[180:181], off
	v_lshl_add_u64 v[180:181], s[84:85], 0, v[146:147]
	s_add_i32 m0, s23, 0xe000
	s_nop 0
	global_load_lds_dwordx4 v[180:181], off
	s_waitcnt vmcnt(8)
	s_waitcnt lgkmcnt(0)
	s_setprio 1
	s_barrier
	v_mfma_f32_16x16x32_bf16 v[128:131], v[132:135], v[176:179], v[128:131]
	v_mfma_f32_16x16x32_bf16 v[124:127], v[148:151], v[176:179], v[124:127]
	v_mfma_f32_16x16x32_bf16 v[112:115], v[132:135], v[220:223], v[112:115]
	v_mfma_f32_16x16x32_bf16 v[108:111], v[148:151], v[220:223], v[108:111]
	v_mfma_f32_16x16x32_bf16 v[92:95], v[132:135], v[228:231], v[92:95]
	v_mfma_f32_16x16x32_bf16 v[88:91], v[148:151], v[228:231], v[88:91]
	v_mfma_f32_16x16x32_bf16 v[76:79], v[132:135], v[236:239], v[76:79]
	v_mfma_f32_16x16x32_bf16 v[72:75], v[148:151], v[236:239], v[72:75]
	v_mfma_f32_16x16x32_bf16 v[128:131], v[136:139], v[188:191], v[128:131]
	v_mfma_f32_16x16x32_bf16 v[124:127], v[152:155], v[188:191], v[124:127]
	v_mfma_f32_16x16x32_bf16 v[112:115], v[136:139], v[224:227], v[112:115]
	v_mfma_f32_16x16x32_bf16 v[108:111], v[152:155], v[224:227], v[108:111]
	v_mfma_f32_16x16x32_bf16 v[92:95], v[136:139], v[232:235], v[92:95]
	v_mfma_f32_16x16x32_bf16 v[88:91], v[152:155], v[232:235], v[88:91]
	v_mfma_f32_16x16x32_bf16 v[76:79], v[136:139], v[240:243], v[76:79]
	v_mfma_f32_16x16x32_bf16 v[72:75], v[152:155], v[240:243], v[72:75]
	v_mfma_f32_16x16x32_bf16 v[120:123], v[156:159], v[176:179], v[120:123]
	v_mfma_f32_16x16x32_bf16 v[116:119], v[168:171], v[176:179], v[116:119]
	v_mfma_f32_16x16x32_bf16 v[104:107], v[156:159], v[220:223], v[104:107]
	v_mfma_f32_16x16x32_bf16 v[100:103], v[168:171], v[220:223], v[100:103]
	v_mfma_f32_16x16x32_bf16 v[84:87], v[156:159], v[228:231], v[84:87]
	v_mfma_f32_16x16x32_bf16 v[80:83], v[168:171], v[228:231], v[80:83]
	v_mfma_f32_16x16x32_bf16 v[68:71], v[156:159], v[236:239], v[68:71]
	v_mfma_f32_16x16x32_bf16 v[64:67], v[168:171], v[236:239], v[64:67]
	v_mfma_f32_16x16x32_bf16 v[120:123], v[164:167], v[188:191], v[120:123]
	v_mfma_f32_16x16x32_bf16 v[116:119], v[172:175], v[188:191], v[116:119]
	v_mfma_f32_16x16x32_bf16 v[104:107], v[164:167], v[224:227], v[104:107]
	v_mfma_f32_16x16x32_bf16 v[100:103], v[172:175], v[224:227], v[100:103]
	v_mfma_f32_16x16x32_bf16 v[84:87], v[164:167], v[232:235], v[84:87]
	v_mfma_f32_16x16x32_bf16 v[80:83], v[172:175], v[232:235], v[80:83]
	v_mfma_f32_16x16x32_bf16 v[68:71], v[164:167], v[240:243], v[68:71]
	v_mfma_f32_16x16x32_bf16 v[64:67], v[172:175], v[240:243], v[64:67]
	s_barrier
	s_setprio 0
	s_add_i32 s66, s97, s10
	v_lshl_add_u64 v[180:181], vcc, 0, v[98:99]
	s_mov_b32 m0, s66
	ds_read_b128 v[176:179], v163 offset:16384
	ds_read_b128 v[188:191], v163 offset:17408
	ds_read_b128 v[220:223], v163 offset:18432
	ds_read_b128 v[224:227], v163 offset:19456
	ds_read_b128 v[228:231], v163 offset:20480
	ds_read_b128 v[232:235], v163 offset:21504
	ds_read_b128 v[236:239], v163 offset:22528
	ds_read_b128 v[240:243], v163 offset:23552
	global_load_lds_dwordx4 v[180:181], off
	s_add_i32 m0, s66, 0x2000
	v_lshl_add_u64 v[192:193], vcc, 0, v[142:143]
	s_add_u32 vcc_lo, vcc_lo, s72
	s_addc_u32 vcc_hi, vcc_hi, 0
	s_add_i32 s0, s0, s10
	global_load_lds_dwordx4 v[192:193], off
	v_lshl_add_u64 v[244:245], vcc, 0, v[98:99]
	s_mov_b32 m0, s0
	v_lshl_add_u64 v[246:247], vcc, 0, v[142:143]
	global_load_lds_dwordx4 v[244:245], off
	s_add_i32 m0, s0, 0x2000
	v_lshl_add_u64 v[248:249], s[86:87], 0, v[96:97]
	global_load_lds_dwordx4 v[246:247], off
	s_mov_b32 m0, s23
	v_lshl_add_u64 v[250:251], s[86:87], 0, v[140:141]
	global_load_lds_dwordx4 v[248:249], off
	s_mov_b32 m0, s33
	s_nop 0
	global_load_lds_dwordx4 v[250:251], off
	s_waitcnt vmcnt(8)
	s_waitcnt lgkmcnt(0)
	s_setprio 1
	s_barrier
	v_mfma_f32_16x16x32_bf16 v[60:63], v[132:135], v[176:179], v[60:63]
	v_mfma_f32_16x16x32_bf16 v[56:59], v[148:151], v[176:179], v[56:59]
	v_mfma_f32_16x16x32_bf16 v[44:47], v[132:135], v[220:223], v[44:47]
	v_mfma_f32_16x16x32_bf16 v[40:43], v[148:151], v[220:223], v[40:43]
	v_mfma_f32_16x16x32_bf16 v[28:31], v[132:135], v[228:231], v[28:31]
	v_mfma_f32_16x16x32_bf16 v[24:27], v[148:151], v[228:231], v[24:27]
	v_mfma_f32_16x16x32_bf16 v[12:15], v[132:135], v[236:239], v[12:15]
	v_mfma_f32_16x16x32_bf16 v[8:11], v[148:151], v[236:239], v[8:11]
	v_mfma_f32_16x16x32_bf16 v[60:63], v[136:139], v[188:191], v[60:63]
	v_mfma_f32_16x16x32_bf16 v[56:59], v[152:155], v[188:191], v[56:59]
	v_mfma_f32_16x16x32_bf16 v[44:47], v[136:139], v[224:227], v[44:47]
	v_mfma_f32_16x16x32_bf16 v[40:43], v[152:155], v[224:227], v[40:43]
	v_mfma_f32_16x16x32_bf16 v[28:31], v[136:139], v[232:235], v[28:31]
	v_mfma_f32_16x16x32_bf16 v[24:27], v[152:155], v[232:235], v[24:27]
	v_mfma_f32_16x16x32_bf16 v[12:15], v[136:139], v[240:243], v[12:15]
	v_mfma_f32_16x16x32_bf16 v[8:11], v[152:155], v[240:243], v[8:11]
	v_mfma_f32_16x16x32_bf16 v[52:55], v[156:159], v[176:179], v[52:55]
	v_mfma_f32_16x16x32_bf16 v[48:51], v[168:171], v[176:179], v[48:51]
	v_mfma_f32_16x16x32_bf16 v[36:39], v[156:159], v[220:223], v[36:39]
	v_mfma_f32_16x16x32_bf16 v[32:35], v[168:171], v[220:223], v[32:35]
	v_mfma_f32_16x16x32_bf16 v[20:23], v[156:159], v[228:231], v[20:23]
	v_mfma_f32_16x16x32_bf16 v[16:19], v[168:171], v[228:231], v[16:19]
	v_mfma_f32_16x16x32_bf16 v[4:7], v[156:159], v[236:239], v[4:7]
	v_mfma_f32_16x16x32_bf16 v[0:3], v[168:171], v[236:239], v[0:3]
	v_mfma_f32_16x16x32_bf16 v[52:55], v[164:167], v[188:191], v[52:55]
	v_mfma_f32_16x16x32_bf16 v[48:51], v[172:175], v[188:191], v[48:51]
	v_mfma_f32_16x16x32_bf16 v[36:39], v[164:167], v[224:227], v[36:39]
	v_mfma_f32_16x16x32_bf16 v[32:35], v[172:175], v[224:227], v[32:35]
	v_mfma_f32_16x16x32_bf16 v[20:23], v[164:167], v[232:235], v[20:23]
	v_mfma_f32_16x16x32_bf16 v[16:19], v[172:175], v[232:235], v[16:19]
	v_mfma_f32_16x16x32_bf16 v[4:7], v[164:167], v[240:243], v[4:7]
	v_mfma_f32_16x16x32_bf16 v[0:3], v[172:175], v[240:243], v[0:3]
	s_barrier
	s_setprio 0
	s_add_i32 s0, 0, 0x18000
	s_add_i32 s66, 0, 0x1c000
	v_add_u32_e32 v152, s0, v161
	v_add_u32_e32 v172, s66, v161
	ds_read_b128 v[132:135], v152
	ds_read_b128 v[136:139], v152 offset:1024
	ds_read_b128 v[148:151], v152 offset:2048
	ds_read_b128 v[152:155], v152 offset:3072
	ds_read_b128 v[156:159], v172
	ds_read_b128 v[164:167], v172 offset:1024
	ds_read_b128 v[168:171], v172 offset:2048
	ds_read_b128 v[172:175], v172 offset:3072
	s_add_u32 s86, s86, s72
	s_addc_u32 s87, s87, 0
	s_mov_b32 m0, s43
	v_lshl_add_u64 v[252:253], s[86:87], 0, v[96:97]
	ds_read_b128 v[176:179], v163 offset:32768
	ds_read_b128 v[188:191], v163 offset:33792
	ds_read_b128 v[220:223], v163 offset:34816
	ds_read_b128 v[224:227], v163 offset:35840
	ds_read_b128 v[228:231], v163 offset:36864
	ds_read_b128 v[232:235], v163 offset:37888
	ds_read_b128 v[236:239], v163 offset:38912
	ds_read_b128 v[240:243], v163 offset:39936
	global_load_lds_dwordx4 v[252:253], off
	v_lshl_add_u64 v[252:253], s[86:87], 0, v[140:141]
	s_mov_b32 m0, s44
	s_nop 0
	global_load_lds_dwordx4 v[252:253], off
	s_waitcnt vmcnt(8)
	s_waitcnt lgkmcnt(0)
	s_setprio 1
	s_barrier
	v_mfma_f32_16x16x32_bf16 v[128:131], v[132:135], v[176:179], v[128:131]
	v_mfma_f32_16x16x32_bf16 v[124:127], v[148:151], v[176:179], v[124:127]
	v_mfma_f32_16x16x32_bf16 v[112:115], v[132:135], v[220:223], v[112:115]
	v_mfma_f32_16x16x32_bf16 v[108:111], v[148:151], v[220:223], v[108:111]
	v_mfma_f32_16x16x32_bf16 v[92:95], v[132:135], v[228:231], v[92:95]
	v_mfma_f32_16x16x32_bf16 v[88:91], v[148:151], v[228:231], v[88:91]
	v_mfma_f32_16x16x32_bf16 v[76:79], v[132:135], v[236:239], v[76:79]
	v_mfma_f32_16x16x32_bf16 v[72:75], v[148:151], v[236:239], v[72:75]
	v_mfma_f32_16x16x32_bf16 v[128:131], v[136:139], v[188:191], v[128:131]
	v_mfma_f32_16x16x32_bf16 v[124:127], v[152:155], v[188:191], v[124:127]
	v_mfma_f32_16x16x32_bf16 v[112:115], v[136:139], v[224:227], v[112:115]
	v_mfma_f32_16x16x32_bf16 v[108:111], v[152:155], v[224:227], v[108:111]
	v_mfma_f32_16x16x32_bf16 v[92:95], v[136:139], v[232:235], v[92:95]
	v_mfma_f32_16x16x32_bf16 v[88:91], v[152:155], v[232:235], v[88:91]
	v_mfma_f32_16x16x32_bf16 v[76:79], v[136:139], v[240:243], v[76:79]
	v_mfma_f32_16x16x32_bf16 v[72:75], v[152:155], v[240:243], v[72:75]
	v_mfma_f32_16x16x32_bf16 v[120:123], v[156:159], v[176:179], v[120:123]
	v_mfma_f32_16x16x32_bf16 v[116:119], v[168:171], v[176:179], v[116:119]
	v_mfma_f32_16x16x32_bf16 v[104:107], v[156:159], v[220:223], v[104:107]
	v_mfma_f32_16x16x32_bf16 v[100:103], v[168:171], v[220:223], v[100:103]
	v_mfma_f32_16x16x32_bf16 v[84:87], v[156:159], v[228:231], v[84:87]
	v_mfma_f32_16x16x32_bf16 v[80:83], v[168:171], v[228:231], v[80:83]
	v_mfma_f32_16x16x32_bf16 v[68:71], v[156:159], v[236:239], v[68:71]
	v_mfma_f32_16x16x32_bf16 v[64:67], v[168:171], v[236:239], v[64:67]
	v_mfma_f32_16x16x32_bf16 v[120:123], v[164:167], v[188:191], v[120:123]
	v_mfma_f32_16x16x32_bf16 v[116:119], v[172:175], v[188:191], v[116:119]
	v_mfma_f32_16x16x32_bf16 v[104:107], v[164:167], v[224:227], v[104:107]
	v_mfma_f32_16x16x32_bf16 v[100:103], v[172:175], v[224:227], v[100:103]
	v_mfma_f32_16x16x32_bf16 v[84:87], v[164:167], v[232:235], v[84:87]
	v_mfma_f32_16x16x32_bf16 v[80:83], v[172:175], v[232:235], v[80:83]
	v_mfma_f32_16x16x32_bf16 v[68:71], v[164:167], v[240:243], v[68:71]
	v_mfma_f32_16x16x32_bf16 v[64:67], v[172:175], v[240:243], v[64:67]
	s_barrier
	s_setprio 0
	s_add_i32 s0, s0, s10
	v_lshl_add_u64 v[180:181], v[180:181], 0, s[58:59]
	s_mov_b32 m0, s0
	ds_read_b128 v[176:179], v163 offset:49152
	ds_read_b128 v[188:191], v163 offset:50176
	ds_read_b128 v[220:223], v163 offset:51200
	ds_read_b128 v[224:227], v163 offset:52224
	ds_read_b128 v[228:231], v163 offset:53248
	ds_read_b128 v[232:235], v163 offset:54272
	ds_read_b128 v[236:239], v163 offset:55296
	ds_read_b128 v[240:243], v163 offset:56320
	global_load_lds_dwordx4 v[180:181], off
	v_lshl_add_u64 v[180:181], v[192:193], 0, s[58:59]
	s_add_i32 m0, s0, 0x2000
	s_add_i32 s0, s66, s10
	global_load_lds_dwordx4 v[180:181], off
	v_lshl_add_u64 v[180:181], v[244:245], 0, s[58:59]
	s_mov_b32 m0, s0
	s_nop 0
	global_load_lds_dwordx4 v[180:181], off
	v_lshl_add_u64 v[180:181], v[246:247], 0, s[58:59]
	s_add_i32 m0, s0, 0x2000
	s_nop 0
	global_load_lds_dwordx4 v[180:181], off
	v_lshl_add_u64 v[180:181], v[248:249], 0, s[58:59]
	s_mov_b32 m0, s47
	s_nop 0
	global_load_lds_dwordx4 v[180:181], off
	v_lshl_add_u64 v[180:181], v[250:251], 0, s[58:59]
	s_mov_b32 m0, s56
	s_nop 0
	global_load_lds_dwordx4 v[180:181], off
	s_waitcnt vmcnt(8)
	s_waitcnt lgkmcnt(0)
	s_setprio 1
	s_barrier
	v_mfma_f32_16x16x32_bf16 v[60:63], v[132:135], v[176:179], v[60:63]
	v_mfma_f32_16x16x32_bf16 v[56:59], v[148:151], v[176:179], v[56:59]
	v_mfma_f32_16x16x32_bf16 v[44:47], v[132:135], v[220:223], v[44:47]
	v_mfma_f32_16x16x32_bf16 v[40:43], v[148:151], v[220:223], v[40:43]
	v_mfma_f32_16x16x32_bf16 v[28:31], v[132:135], v[228:231], v[28:31]
	v_mfma_f32_16x16x32_bf16 v[24:27], v[148:151], v[228:231], v[24:27]
	v_mfma_f32_16x16x32_bf16 v[12:15], v[132:135], v[236:239], v[12:15]
	v_mfma_f32_16x16x32_bf16 v[8:11], v[148:151], v[236:239], v[8:11]
	v_mfma_f32_16x16x32_bf16 v[60:63], v[136:139], v[188:191], v[60:63]
	v_mfma_f32_16x16x32_bf16 v[56:59], v[152:155], v[188:191], v[56:59]
	v_mfma_f32_16x16x32_bf16 v[44:47], v[136:139], v[224:227], v[44:47]
	v_mfma_f32_16x16x32_bf16 v[40:43], v[152:155], v[224:227], v[40:43]
	v_mfma_f32_16x16x32_bf16 v[28:31], v[136:139], v[232:235], v[28:31]
	v_mfma_f32_16x16x32_bf16 v[24:27], v[152:155], v[232:235], v[24:27]
	v_mfma_f32_16x16x32_bf16 v[12:15], v[136:139], v[240:243], v[12:15]
	v_mfma_f32_16x16x32_bf16 v[8:11], v[152:155], v[240:243], v[8:11]
	v_mfma_f32_16x16x32_bf16 v[52:55], v[156:159], v[176:179], v[52:55]
	v_mfma_f32_16x16x32_bf16 v[48:51], v[168:171], v[176:179], v[48:51]
	v_mfma_f32_16x16x32_bf16 v[36:39], v[156:159], v[220:223], v[36:39]
	v_mfma_f32_16x16x32_bf16 v[32:35], v[168:171], v[220:223], v[32:35]
	v_mfma_f32_16x16x32_bf16 v[20:23], v[156:159], v[228:231], v[20:23]
	v_mfma_f32_16x16x32_bf16 v[16:19], v[168:171], v[228:231], v[16:19]
	v_mfma_f32_16x16x32_bf16 v[4:7], v[156:159], v[236:239], v[4:7]
	v_mfma_f32_16x16x32_bf16 v[0:3], v[168:171], v[236:239], v[0:3]
	v_mfma_f32_16x16x32_bf16 v[52:55], v[164:167], v[188:191], v[52:55]
	v_mfma_f32_16x16x32_bf16 v[48:51], v[172:175], v[188:191], v[48:51]
	v_mfma_f32_16x16x32_bf16 v[36:39], v[164:167], v[224:227], v[36:39]
	v_mfma_f32_16x16x32_bf16 v[32:35], v[172:175], v[224:227], v[32:35]
	v_mfma_f32_16x16x32_bf16 v[20:23], v[164:167], v[232:235], v[20:23]
	v_mfma_f32_16x16x32_bf16 v[16:19], v[172:175], v[232:235], v[16:19]
	v_mfma_f32_16x16x32_bf16 v[4:7], v[164:167], v[240:243], v[4:7]
	v_mfma_f32_16x16x32_bf16 v[0:3], v[172:175], v[240:243], v[0:3]
	s_barrier
	s_setprio 0
	s_add_u32 s84, s84, 0x100
	s_addc_u32 s85, s85, 0
	s_add_u32 s26, s26, 0x100
	s_addc_u32 s27, s27, 0
	s_cmp_ge_u32 s42, s67
	s_mov_b32 s0, s42
	s_cbranch_scc0 .LBB0_310

.LBB0_345:
	s_ashr_i32 s71, s70, 31
	s_lshl_b64 s[56:57], s[70:71], 19
	s_add_u32 s74, s12, s56
	s_addc_u32 s75, s13, s57
	s_and_b64 s[56:57], s[72:73], exec
	s_cselect_b32 s27, s75, s79
	s_cselect_b32 s42, s74, s78
	s_ashr_i32 s69, s68, 31
	s_lshl_b64 s[56:57], s[68:69], 19
	s_add_u32 s76, s4, s56
	s_addc_u32 s77, s5, s57
	s_and_b64 s[56:57], s[72:73], exec
	s_cselect_b32 s56, s77, s81
	s_cselect_b32 s57, s76, s80
	s_add_u32 s78, s78, 0x40080
	s_addc_u32 s79, s79, 0
	s_add_u32 s69, s80, 0x100
	s_addc_u32 s71, s81, 0
	s_mov_b32 s84, -2
	s_waitcnt vmcnt(0)
	s_add_u32 s80, s78, 0xfffc0080
	s_addc_u32 s81, s79, -1
	s_add_i32 s85, 0, 0x10000
	s_cmp_eq_u32 s84, 12
	s_cselect_b32 s83, s27, s81
	s_cselect_b32 s82, s42, s80
	s_cselect_b32 s81, s56, s71
	s_cselect_b32 s80, s57, s69
	s_add_i32 s88, 0, 0x14000
	v_add_u32_e32 v160, s85, v145
	v_add_u32_e32 v176, s88, v145
	ds_read_b128 v[140:143], v160
	ds_read_b128 v[152:155], v160 offset:1024
	ds_read_b128 v[156:159], v160 offset:2048
	ds_read_b128 v[160:163], v160 offset:3072
	ds_read_b128 v[164:167], v176
	ds_read_b128 v[168:171], v176 offset:1024
	ds_read_b128 v[172:175], v176 offset:2048
	ds_read_b128 v[176:179], v176 offset:3072
	v_lshl_add_u64 v[180:181], s[78:79], 0, v[136:137]
	s_add_i32 m0, s11, 0xc000
	ds_read_b128 v[188:191], v151
	ds_read_b128 v[220:223], v151 offset:1024
	ds_read_b128 v[224:227], v151 offset:2048
	ds_read_b128 v[228:231], v151 offset:3072
	ds_read_b128 v[232:235], v151 offset:4096
	ds_read_b128 v[236:239], v151 offset:5120
	ds_read_b128 v[240:243], v151 offset:6144
	ds_read_b128 v[244:247], v151 offset:7168
	global_load_lds_dwordx4 v[180:181], off
	v_lshl_add_u64 v[180:181], s[78:79], 0, v[138:139]
	s_add_i32 m0, s11, 0xe000
	s_nop 0
	global_load_lds_dwordx4 v[180:181], off
	s_waitcnt vmcnt(8)
	s_waitcnt lgkmcnt(0)
	s_setprio 1
	s_barrier
	v_mfma_f32_16x16x32_bf16 v[128:131], v[140:143], v[188:191], 0
	v_mfma_f32_16x16x32_bf16 v[120:123], v[156:159], v[188:191], 0
	v_mfma_f32_16x16x32_bf16 v[112:115], v[140:143], v[224:227], 0
	v_mfma_f32_16x16x32_bf16 v[104:107], v[156:159], v[224:227], 0
	v_mfma_f32_16x16x32_bf16 v[92:95], v[140:143], v[232:235], 0
	v_mfma_f32_16x16x32_bf16 v[84:87], v[156:159], v[232:235], 0
	v_mfma_f32_16x16x32_bf16 v[76:79], v[140:143], v[240:243], 0
	v_mfma_f32_16x16x32_bf16 v[68:71], v[156:159], v[240:243], 0
	v_mfma_f32_16x16x32_bf16 v[128:131], v[152:155], v[220:223], v[128:131]
	v_mfma_f32_16x16x32_bf16 v[120:123], v[160:163], v[220:223], v[120:123]
	v_mfma_f32_16x16x32_bf16 v[112:115], v[152:155], v[228:231], v[112:115]
	v_mfma_f32_16x16x32_bf16 v[104:107], v[160:163], v[228:231], v[104:107]
	v_mfma_f32_16x16x32_bf16 v[92:95], v[152:155], v[236:239], v[92:95]
	v_mfma_f32_16x16x32_bf16 v[84:87], v[160:163], v[236:239], v[84:87]
	v_mfma_f32_16x16x32_bf16 v[76:79], v[152:155], v[244:247], v[76:79]
	v_mfma_f32_16x16x32_bf16 v[68:71], v[160:163], v[244:247], v[68:71]
	v_mfma_f32_16x16x32_bf16 v[124:127], v[164:167], v[188:191], 0
	v_mfma_f32_16x16x32_bf16 v[116:119], v[172:175], v[188:191], 0
	v_mfma_f32_16x16x32_bf16 v[108:111], v[164:167], v[224:227], 0
	v_mfma_f32_16x16x32_bf16 v[100:103], v[172:175], v[224:227], 0
	v_mfma_f32_16x16x32_bf16 v[88:91], v[164:167], v[232:235], 0
	v_mfma_f32_16x16x32_bf16 v[80:83], v[172:175], v[232:235], 0
	v_mfma_f32_16x16x32_bf16 v[72:75], v[164:167], v[240:243], 0
	v_mfma_f32_16x16x32_bf16 v[64:67], v[172:175], v[240:243], 0
	v_mfma_f32_16x16x32_bf16 v[124:127], v[168:171], v[220:223], v[124:127]
	v_mfma_f32_16x16x32_bf16 v[116:119], v[176:179], v[220:223], v[116:119]
	v_mfma_f32_16x16x32_bf16 v[108:111], v[168:171], v[228:231], v[108:111]
	v_mfma_f32_16x16x32_bf16 v[100:103], v[176:179], v[228:231], v[100:103]
	v_mfma_f32_16x16x32_bf16 v[88:91], v[168:171], v[236:239], v[88:91]
	v_mfma_f32_16x16x32_bf16 v[80:83], v[176:179], v[236:239], v[80:83]
	v_mfma_f32_16x16x32_bf16 v[72:75], v[168:171], v[244:247], v[72:75]
	v_mfma_f32_16x16x32_bf16 v[64:67], v[176:179], v[244:247], v[64:67]
	s_barrier
	s_setprio 0
	s_add_i32 s85, s85, s10
	v_lshl_add_u64 v[180:181], s[80:81], 0, v[98:99]
	s_mov_b32 m0, s85
	ds_read_b128 v[188:191], v151 offset:16384
	ds_read_b128 v[220:223], v151 offset:17408
	ds_read_b128 v[224:227], v151 offset:18432
	ds_read_b128 v[228:231], v151 offset:19456
	ds_read_b128 v[232:235], v151 offset:20480
	ds_read_b128 v[236:239], v151 offset:21504
	ds_read_b128 v[240:243], v151 offset:22528
	ds_read_b128 v[244:247], v151 offset:23552
	global_load_lds_dwordx4 v[180:181], off
	s_add_i32 m0, s85, 0x2000
	s_add_u32 s86, s80, 0x40000
	v_lshl_add_u64 v[192:193], s[80:81], 0, v[134:135]
	s_addc_u32 s87, s81, 0
	s_add_i32 s85, s88, s10
	global_load_lds_dwordx4 v[192:193], off
	v_lshl_add_u64 v[248:249], s[86:87], 0, v[98:99]
	s_mov_b32 m0, s85
	v_lshl_add_u64 v[250:251], s[82:83], 0, v[132:133]
	global_load_lds_dwordx4 v[248:249], off
	v_lshl_add_u64 v[248:249], s[86:87], 0, v[134:135]
	s_add_i32 m0, s85, 0x2000
	s_nop 0
	global_load_lds_dwordx4 v[248:249], off
	v_lshl_add_u64 v[248:249], s[82:83], 0, v[96:97]
	s_mov_b32 m0, s11
	s_nop 0
	global_load_lds_dwordx4 v[248:249], off
	s_mov_b32 m0, s20
	s_nop 0
	global_load_lds_dwordx4 v[250:251], off
	s_waitcnt vmcnt(8)
	s_waitcnt lgkmcnt(0)
	s_setprio 1
	s_barrier
	v_mfma_f32_16x16x32_bf16 v[60:63], v[140:143], v[188:191], 0
	v_mfma_f32_16x16x32_bf16 v[52:55], v[156:159], v[188:191], 0
	v_mfma_f32_16x16x32_bf16 v[44:47], v[140:143], v[224:227], 0
	v_mfma_f32_16x16x32_bf16 v[36:39], v[156:159], v[224:227], 0
	v_mfma_f32_16x16x32_bf16 v[28:31], v[140:143], v[232:235], 0
	v_mfma_f32_16x16x32_bf16 v[20:23], v[156:159], v[232:235], 0
	v_mfma_f32_16x16x32_bf16 v[12:15], v[140:143], v[240:243], 0
	v_mfma_f32_16x16x32_bf16 v[4:7], v[156:159], v[240:243], 0
	v_mfma_f32_16x16x32_bf16 v[60:63], v[152:155], v[220:223], v[60:63]
	v_mfma_f32_16x16x32_bf16 v[52:55], v[160:163], v[220:223], v[52:55]
	v_mfma_f32_16x16x32_bf16 v[44:47], v[152:155], v[228:231], v[44:47]
	v_mfma_f32_16x16x32_bf16 v[36:39], v[160:163], v[228:231], v[36:39]
	v_mfma_f32_16x16x32_bf16 v[28:31], v[152:155], v[236:239], v[28:31]
	v_mfma_f32_16x16x32_bf16 v[20:23], v[160:163], v[236:239], v[20:23]
	v_mfma_f32_16x16x32_bf16 v[12:15], v[152:155], v[244:247], v[12:15]
	v_mfma_f32_16x16x32_bf16 v[4:7], v[160:163], v[244:247], v[4:7]
	v_mfma_f32_16x16x32_bf16 v[56:59], v[164:167], v[188:191], 0
	v_mfma_f32_16x16x32_bf16 v[48:51], v[172:175], v[188:191], 0
	v_mfma_f32_16x16x32_bf16 v[40:43], v[164:167], v[224:227], 0
	v_mfma_f32_16x16x32_bf16 v[32:35], v[172:175], v[224:227], 0
	v_mfma_f32_16x16x32_bf16 v[24:27], v[164:167], v[232:235], 0
	v_mfma_f32_16x16x32_bf16 v[16:19], v[172:175], v[232:235], 0
	v_mfma_f32_16x16x32_bf16 v[8:11], v[164:167], v[240:243], 0
	v_mfma_f32_16x16x32_bf16 v[0:3], v[172:175], v[240:243], 0
	v_mfma_f32_16x16x32_bf16 v[56:59], v[168:171], v[220:223], v[56:59]
	v_mfma_f32_16x16x32_bf16 v[48:51], v[176:179], v[220:223], v[48:51]
	v_mfma_f32_16x16x32_bf16 v[40:43], v[168:171], v[228:231], v[40:43]
	v_mfma_f32_16x16x32_bf16 v[32:35], v[176:179], v[228:231], v[32:35]
	v_mfma_f32_16x16x32_bf16 v[24:27], v[168:171], v[236:239], v[24:27]
	v_mfma_f32_16x16x32_bf16 v[16:19], v[176:179], v[236:239], v[16:19]
	v_mfma_f32_16x16x32_bf16 v[8:11], v[168:171], v[244:247], v[8:11]
	v_mfma_f32_16x16x32_bf16 v[0:3], v[176:179], v[244:247], v[0:3]
	s_barrier
	s_setprio 0
	s_add_i32 s85, 0, 0x18000
	s_add_i32 s86, 0, 0x1c000
	v_add_u32_e32 v160, s85, v145
	v_add_u32_e32 v176, s86, v145
	ds_read_b128 v[140:143], v160
	ds_read_b128 v[152:155], v160 offset:1024
	ds_read_b128 v[156:159], v160 offset:2048
	ds_read_b128 v[160:163], v160 offset:3072
	ds_read_b128 v[164:167], v176
	ds_read_b128 v[168:171], v176 offset:1024
	ds_read_b128 v[172:175], v176 offset:2048
	ds_read_b128 v[176:179], v176 offset:3072
	s_add_u32 s82, s82, 0x40000
	s_addc_u32 s83, s83, 0
	s_mov_b32 m0, s22
	v_lshl_add_u64 v[252:253], s[82:83], 0, v[96:97]
	ds_read_b128 v[188:191], v151 offset:32768
	ds_read_b128 v[220:223], v151 offset:33792
	ds_read_b128 v[224:227], v151 offset:34816
	ds_read_b128 v[228:231], v151 offset:35840
	ds_read_b128 v[232:235], v151 offset:36864
	ds_read_b128 v[236:239], v151 offset:37888
	ds_read_b128 v[240:243], v151 offset:38912
	ds_read_b128 v[244:247], v151 offset:39936
	global_load_lds_dwordx4 v[252:253], off
	v_lshl_add_u64 v[252:253], s[82:83], 0, v[132:133]
	s_mov_b32 m0, s23
	s_nop 0
	global_load_lds_dwordx4 v[252:253], off
	s_waitcnt vmcnt(8)
	s_waitcnt lgkmcnt(0)
	s_setprio 1
	s_barrier
	v_mfma_f32_16x16x32_bf16 v[128:131], v[140:143], v[188:191], v[128:131]
	v_mfma_f32_16x16x32_bf16 v[120:123], v[156:159], v[188:191], v[120:123]
	v_mfma_f32_16x16x32_bf16 v[112:115], v[140:143], v[224:227], v[112:115]
	v_mfma_f32_16x16x32_bf16 v[104:107], v[156:159], v[224:227], v[104:107]
	v_mfma_f32_16x16x32_bf16 v[92:95], v[140:143], v[232:235], v[92:95]
	v_mfma_f32_16x16x32_bf16 v[84:87], v[156:159], v[232:235], v[84:87]
	v_mfma_f32_16x16x32_bf16 v[76:79], v[140:143], v[240:243], v[76:79]
	v_mfma_f32_16x16x32_bf16 v[68:71], v[156:159], v[240:243], v[68:71]
	v_mfma_f32_16x16x32_bf16 v[128:131], v[152:155], v[220:223], v[128:131]
	v_mfma_f32_16x16x32_bf16 v[120:123], v[160:163], v[220:223], v[120:123]
	v_mfma_f32_16x16x32_bf16 v[112:115], v[152:155], v[228:231], v[112:115]
	v_mfma_f32_16x16x32_bf16 v[104:107], v[160:163], v[228:231], v[104:107]
	v_mfma_f32_16x16x32_bf16 v[92:95], v[152:155], v[236:239], v[92:95]
	v_mfma_f32_16x16x32_bf16 v[84:87], v[160:163], v[236:239], v[84:87]
	v_mfma_f32_16x16x32_bf16 v[76:79], v[152:155], v[244:247], v[76:79]
	v_mfma_f32_16x16x32_bf16 v[68:71], v[160:163], v[244:247], v[68:71]
	v_mfma_f32_16x16x32_bf16 v[124:127], v[164:167], v[188:191], v[124:127]
	v_mfma_f32_16x16x32_bf16 v[116:119], v[172:175], v[188:191], v[116:119]
	v_mfma_f32_16x16x32_bf16 v[108:111], v[164:167], v[224:227], v[108:111]
	v_mfma_f32_16x16x32_bf16 v[100:103], v[172:175], v[224:227], v[100:103]
	v_mfma_f32_16x16x32_bf16 v[88:91], v[164:167], v[232:235], v[88:91]
	v_mfma_f32_16x16x32_bf16 v[80:83], v[172:175], v[232:235], v[80:83]
	v_mfma_f32_16x16x32_bf16 v[72:75], v[164:167], v[240:243], v[72:75]
	v_mfma_f32_16x16x32_bf16 v[64:67], v[172:175], v[240:243], v[64:67]
	v_mfma_f32_16x16x32_bf16 v[124:127], v[168:171], v[220:223], v[124:127]
	v_mfma_f32_16x16x32_bf16 v[116:119], v[176:179], v[220:223], v[116:119]
	v_mfma_f32_16x16x32_bf16 v[108:111], v[168:171], v[228:231], v[108:111]
	v_mfma_f32_16x16x32_bf16 v[100:103], v[176:179], v[228:231], v[100:103]
	v_mfma_f32_16x16x32_bf16 v[88:91], v[168:171], v[236:239], v[88:91]
	v_mfma_f32_16x16x32_bf16 v[80:83], v[176:179], v[236:239], v[80:83]
	v_mfma_f32_16x16x32_bf16 v[72:75], v[168:171], v[244:247], v[72:75]
	v_mfma_f32_16x16x32_bf16 v[64:67], v[176:179], v[244:247], v[64:67]
	s_barrier
	s_setprio 0
	s_add_i32 s82, s85, s10
	v_lshl_add_u64 v[180:181], v[180:181], 0, s[58:59]
	s_mov_b32 m0, s82
	ds_read_b128 v[188:191], v151 offset:49152
	ds_read_b128 v[220:223], v151 offset:50176
	ds_read_b128 v[224:227], v151 offset:51200
	ds_read_b128 v[228:231], v151 offset:52224
	ds_read_b128 v[232:235], v151 offset:53248
	ds_read_b128 v[236:239], v151 offset:54272
	ds_read_b128 v[240:243], v151 offset:55296
	ds_read_b128 v[244:247], v151 offset:56320
	global_load_lds_dwordx4 v[180:181], off
	s_add_i32 m0, s82, 0x2000
	s_add_u32 s80, s80, 0x40080
	v_lshl_add_u64 v[180:181], v[192:193], 0, s[58:59]
	s_addc_u32 s81, s81, 0
	s_add_i32 s82, s86, s10
	global_load_lds_dwordx4 v[180:181], off
	v_lshl_add_u64 v[180:181], s[80:81], 0, v[98:99]
	s_mov_b32 m0, s82
	s_nop 0
	global_load_lds_dwordx4 v[180:181], off
	v_lshl_add_u64 v[180:181], s[80:81], 0, v[134:135]
	s_add_i32 m0, s82, 0x2000
	s_nop 0
	global_load_lds_dwordx4 v[180:181], off
	v_lshl_add_u64 v[180:181], v[248:249], 0, s[58:59]
	s_mov_b32 m0, s33
	s_nop 0
	global_load_lds_dwordx4 v[180:181], off
	v_lshl_add_u64 v[180:181], v[250:251], 0, s[58:59]
	s_mov_b32 m0, s43
	s_nop 0
	global_load_lds_dwordx4 v[180:181], off
	s_waitcnt vmcnt(8)
	s_waitcnt lgkmcnt(0)
	s_setprio 1
	s_barrier
	v_mfma_f32_16x16x32_bf16 v[60:63], v[140:143], v[188:191], v[60:63]
	v_mfma_f32_16x16x32_bf16 v[52:55], v[156:159], v[188:191], v[52:55]
	v_mfma_f32_16x16x32_bf16 v[44:47], v[140:143], v[224:227], v[44:47]
	v_mfma_f32_16x16x32_bf16 v[36:39], v[156:159], v[224:227], v[36:39]
	v_mfma_f32_16x16x32_bf16 v[28:31], v[140:143], v[232:235], v[28:31]
	v_mfma_f32_16x16x32_bf16 v[20:23], v[156:159], v[232:235], v[20:23]
	v_mfma_f32_16x16x32_bf16 v[12:15], v[140:143], v[240:243], v[12:15]
	v_mfma_f32_16x16x32_bf16 v[4:7], v[156:159], v[240:243], v[4:7]
	v_mfma_f32_16x16x32_bf16 v[60:63], v[152:155], v[220:223], v[60:63]
	v_mfma_f32_16x16x32_bf16 v[52:55], v[160:163], v[220:223], v[52:55]
	v_mfma_f32_16x16x32_bf16 v[44:47], v[152:155], v[228:231], v[44:47]
	v_mfma_f32_16x16x32_bf16 v[36:39], v[160:163], v[228:231], v[36:39]
	v_mfma_f32_16x16x32_bf16 v[28:31], v[152:155], v[236:239], v[28:31]
	v_mfma_f32_16x16x32_bf16 v[20:23], v[160:163], v[236:239], v[20:23]
	v_mfma_f32_16x16x32_bf16 v[12:15], v[152:155], v[244:247], v[12:15]
	v_mfma_f32_16x16x32_bf16 v[4:7], v[160:163], v[244:247], v[4:7]
	v_mfma_f32_16x16x32_bf16 v[56:59], v[164:167], v[188:191], v[56:59]
	v_mfma_f32_16x16x32_bf16 v[48:51], v[172:175], v[188:191], v[48:51]
	v_mfma_f32_16x16x32_bf16 v[40:43], v[164:167], v[224:227], v[40:43]
	v_mfma_f32_16x16x32_bf16 v[32:35], v[172:175], v[224:227], v[32:35]
	v_mfma_f32_16x16x32_bf16 v[24:27], v[164:167], v[232:235], v[24:27]
	v_mfma_f32_16x16x32_bf16 v[16:19], v[172:175], v[232:235], v[16:19]
	v_mfma_f32_16x16x32_bf16 v[8:11], v[164:167], v[240:243], v[8:11]
	v_mfma_f32_16x16x32_bf16 v[0:3], v[172:175], v[240:243], v[0:3]
	v_mfma_f32_16x16x32_bf16 v[56:59], v[168:171], v[220:223], v[56:59]
	v_mfma_f32_16x16x32_bf16 v[48:51], v[176:179], v[220:223], v[48:51]
	v_mfma_f32_16x16x32_bf16 v[40:43], v[168:171], v[228:231], v[40:43]
	v_mfma_f32_16x16x32_bf16 v[32:35], v[176:179], v[228:231], v[32:35]
	v_mfma_f32_16x16x32_bf16 v[24:27], v[168:171], v[236:239], v[24:27]
	v_mfma_f32_16x16x32_bf16 v[16:19], v[176:179], v[236:239], v[16:19]
	v_mfma_f32_16x16x32_bf16 v[8:11], v[168:171], v[244:247], v[8:11]
	v_mfma_f32_16x16x32_bf16 v[0:3], v[176:179], v[244:247], v[0:3]
	s_barrier
	s_setprio 0
	s_add_i32 s84, s84, 2
	s_add_u32 s78, s78, 0x100
	s_addc_u32 s79, s79, 0
	s_add_u32 s69, s69, 0x100
	s_addc_u32 s71, s71, 0
	s_cmp_gt_u32 s84, 13
	s_cbranch_scc1 .Lpeel_exit_346
.LBB0_346:
	s_add_u32 s80, s78, 0xfffc0080
	s_addc_u32 s81, s79, -1
	s_add_i32 s85, 0, 0x10000
	s_cmp_eq_u32 s84, 12
	s_cselect_b32 s83, s27, s81
	s_cselect_b32 s82, s42, s80
	s_cselect_b32 s81, s56, s71
	s_cselect_b32 s80, s57, s69
	s_add_i32 s88, 0, 0x14000
	v_add_u32_e32 v160, s85, v145
	v_add_u32_e32 v176, s88, v145
	ds_read_b128 v[140:143], v160
	ds_read_b128 v[152:155], v160 offset:1024
	ds_read_b128 v[156:159], v160 offset:2048
	ds_read_b128 v[160:163], v160 offset:3072
	ds_read_b128 v[164:167], v176
	ds_read_b128 v[168:171], v176 offset:1024
	ds_read_b128 v[172:175], v176 offset:2048
	ds_read_b128 v[176:179], v176 offset:3072
	v_lshl_add_u64 v[180:181], s[78:79], 0, v[136:137]
	s_add_i32 m0, s11, 0xc000
	ds_read_b128 v[188:191], v151
	ds_read_b128 v[220:223], v151 offset:1024
	ds_read_b128 v[224:227], v151 offset:2048
	ds_read_b128 v[228:231], v151 offset:3072
	ds_read_b128 v[232:235], v151 offset:4096
	ds_read_b128 v[236:239], v151 offset:5120
	ds_read_b128 v[240:243], v151 offset:6144
	ds_read_b128 v[244:247], v151 offset:7168
	global_load_lds_dwordx4 v[180:181], off
	v_lshl_add_u64 v[180:181], s[78:79], 0, v[138:139]
	s_add_i32 m0, s11, 0xe000
	s_nop 0
	global_load_lds_dwordx4 v[180:181], off
	s_waitcnt vmcnt(8)
	s_waitcnt lgkmcnt(0)
	s_setprio 1
	s_barrier
	v_mfma_f32_16x16x32_bf16 v[128:131], v[140:143], v[188:191], v[128:131]
	v_mfma_f32_16x16x32_bf16 v[120:123], v[156:159], v[188:191], v[120:123]
	v_mfma_f32_16x16x32_bf16 v[112:115], v[140:143], v[224:227], v[112:115]
	v_mfma_f32_16x16x32_bf16 v[104:107], v[156:159], v[224:227], v[104:107]
	v_mfma_f32_16x16x32_bf16 v[92:95], v[140:143], v[232:235], v[92:95]
	v_mfma_f32_16x16x32_bf16 v[84:87], v[156:159], v[232:235], v[84:87]
	v_mfma_f32_16x16x32_bf16 v[76:79], v[140:143], v[240:243], v[76:79]
	v_mfma_f32_16x16x32_bf16 v[68:71], v[156:159], v[240:243], v[68:71]
	v_mfma_f32_16x16x32_bf16 v[128:131], v[152:155], v[220:223], v[128:131]
	v_mfma_f32_16x16x32_bf16 v[120:123], v[160:163], v[220:223], v[120:123]
	v_mfma_f32_16x16x32_bf16 v[112:115], v[152:155], v[228:231], v[112:115]
	v_mfma_f32_16x16x32_bf16 v[104:107], v[160:163], v[228:231], v[104:107]
	v_mfma_f32_16x16x32_bf16 v[92:95], v[152:155], v[236:239], v[92:95]
	v_mfma_f32_16x16x32_bf16 v[84:87], v[160:163], v[236:239], v[84:87]
	v_mfma_f32_16x16x32_bf16 v[76:79], v[152:155], v[244:247], v[76:79]
	v_mfma_f32_16x16x32_bf16 v[68:71], v[160:163], v[244:247], v[68:71]
	v_mfma_f32_16x16x32_bf16 v[124:127], v[164:167], v[188:191], v[124:127]
	v_mfma_f32_16x16x32_bf16 v[116:119], v[172:175], v[188:191], v[116:119]
	v_mfma_f32_16x16x32_bf16 v[108:111], v[164:167], v[224:227], v[108:111]
	v_mfma_f32_16x16x32_bf16 v[100:103], v[172:175], v[224:227], v[100:103]
	v_mfma_f32_16x16x32_bf16 v[88:91], v[164:167], v[232:235], v[88:91]
	v_mfma_f32_16x16x32_bf16 v[80:83], v[172:175], v[232:235], v[80:83]
	v_mfma_f32_16x16x32_bf16 v[72:75], v[164:167], v[240:243], v[72:75]
	v_mfma_f32_16x16x32_bf16 v[64:67], v[172:175], v[240:243], v[64:67]
	v_mfma_f32_16x16x32_bf16 v[124:127], v[168:171], v[220:223], v[124:127]
	v_mfma_f32_16x16x32_bf16 v[116:119], v[176:179], v[220:223], v[116:119]
	v_mfma_f32_16x16x32_bf16 v[108:111], v[168:171], v[228:231], v[108:111]
	v_mfma_f32_16x16x32_bf16 v[100:103], v[176:179], v[228:231], v[100:103]
	v_mfma_f32_16x16x32_bf16 v[88:91], v[168:171], v[236:239], v[88:91]
	v_mfma_f32_16x16x32_bf16 v[80:83], v[176:179], v[236:239], v[80:83]
	v_mfma_f32_16x16x32_bf16 v[72:75], v[168:171], v[244:247], v[72:75]
	v_mfma_f32_16x16x32_bf16 v[64:67], v[176:179], v[244:247], v[64:67]
	s_barrier
	s_setprio 0
	s_add_i32 s85, s85, s10
	v_lshl_add_u64 v[180:181], s[80:81], 0, v[98:99]
	s_mov_b32 m0, s85
	ds_read_b128 v[188:191], v151 offset:16384
	ds_read_b128 v[220:223], v151 offset:17408
	ds_read_b128 v[224:227], v151 offset:18432
	ds_read_b128 v[228:231], v151 offset:19456
	ds_read_b128 v[232:235], v151 offset:20480
	ds_read_b128 v[236:239], v151 offset:21504
	ds_read_b128 v[240:243], v151 offset:22528
	ds_read_b128 v[244:247], v151 offset:23552
	global_load_lds_dwordx4 v[180:181], off
	s_add_i32 m0, s85, 0x2000
	s_add_u32 s86, s80, 0x40000
	v_lshl_add_u64 v[192:193], s[80:81], 0, v[134:135]
	s_addc_u32 s87, s81, 0
	s_add_i32 s85, s88, s10
	global_load_lds_dwordx4 v[192:193], off
	v_lshl_add_u64 v[248:249], s[86:87], 0, v[98:99]
	s_mov_b32 m0, s85
	v_lshl_add_u64 v[250:251], s[82:83], 0, v[132:133]
	global_load_lds_dwordx4 v[248:249], off
	v_lshl_add_u64 v[248:249], s[86:87], 0, v[134:135]
	s_add_i32 m0, s85, 0x2000
	s_nop 0
	global_load_lds_dwordx4 v[248:249], off
	v_lshl_add_u64 v[248:249], s[82:83], 0, v[96:97]
	s_mov_b32 m0, s11
	s_nop 0
	global_load_lds_dwordx4 v[248:249], off
	s_mov_b32 m0, s20
	s_nop 0
	global_load_lds_dwordx4 v[250:251], off
	s_waitcnt vmcnt(8)
	s_waitcnt lgkmcnt(0)
	s_setprio 1
	s_barrier
	v_mfma_f32_16x16x32_bf16 v[60:63], v[140:143], v[188:191], v[60:63]
	v_mfma_f32_16x16x32_bf16 v[52:55], v[156:159], v[188:191], v[52:55]
	v_mfma_f32_16x16x32_bf16 v[44:47], v[140:143], v[224:227], v[44:47]
	v_mfma_f32_16x16x32_bf16 v[36:39], v[156:159], v[224:227], v[36:39]
	v_mfma_f32_16x16x32_bf16 v[28:31], v[140:143], v[232:235], v[28:31]
	v_mfma_f32_16x16x32_bf16 v[20:23], v[156:159], v[232:235], v[20:23]
	v_mfma_f32_16x16x32_bf16 v[12:15], v[140:143], v[240:243], v[12:15]
	v_mfma_f32_16x16x32_bf16 v[4:7], v[156:159], v[240:243], v[4:7]
	v_mfma_f32_16x16x32_bf16 v[60:63], v[152:155], v[220:223], v[60:63]
	v_mfma_f32_16x16x32_bf16 v[52:55], v[160:163], v[220:223], v[52:55]
	v_mfma_f32_16x16x32_bf16 v[44:47], v[152:155], v[228:231], v[44:47]
	v_mfma_f32_16x16x32_bf16 v[36:39], v[160:163], v[228:231], v[36:39]
	v_mfma_f32_16x16x32_bf16 v[28:31], v[152:155], v[236:239], v[28:31]
	v_mfma_f32_16x16x32_bf16 v[20:23], v[160:163], v[236:239], v[20:23]
	v_mfma_f32_16x16x32_bf16 v[12:15], v[152:155], v[244:247], v[12:15]
	v_mfma_f32_16x16x32_bf16 v[4:7], v[160:163], v[244:247], v[4:7]
	v_mfma_f32_16x16x32_bf16 v[56:59], v[164:167], v[188:191], v[56:59]
	v_mfma_f32_16x16x32_bf16 v[48:51], v[172:175], v[188:191], v[48:51]
	v_mfma_f32_16x16x32_bf16 v[40:43], v[164:167], v[224:227], v[40:43]
	v_mfma_f32_16x16x32_bf16 v[32:35], v[172:175], v[224:227], v[32:35]
	v_mfma_f32_16x16x32_bf16 v[24:27], v[164:167], v[232:235], v[24:27]
	v_mfma_f32_16x16x32_bf16 v[16:19], v[172:175], v[232:235], v[16:19]
	v_mfma_f32_16x16x32_bf16 v[8:11], v[164:167], v[240:243], v[8:11]
	v_mfma_f32_16x16x32_bf16 v[0:3], v[172:175], v[240:243], v[0:3]
	v_mfma_f32_16x16x32_bf16 v[56:59], v[168:171], v[220:223], v[56:59]
	v_mfma_f32_16x16x32_bf16 v[48:51], v[176:179], v[220:223], v[48:51]
	v_mfma_f32_16x16x32_bf16 v[40:43], v[168:171], v[228:231], v[40:43]
	v_mfma_f32_16x16x32_bf16 v[32:35], v[176:179], v[228:231], v[32:35]
	v_mfma_f32_16x16x32_bf16 v[24:27], v[168:171], v[236:239], v[24:27]
	v_mfma_f32_16x16x32_bf16 v[16:19], v[176:179], v[236:239], v[16:19]
	v_mfma_f32_16x16x32_bf16 v[8:11], v[168:171], v[244:247], v[8:11]
	v_mfma_f32_16x16x32_bf16 v[0:3], v[176:179], v[244:247], v[0:3]
	s_barrier
	s_setprio 0
	s_add_i32 s85, 0, 0x18000
	s_add_i32 s86, 0, 0x1c000
	v_add_u32_e32 v160, s85, v145
	v_add_u32_e32 v176, s86, v145
	ds_read_b128 v[140:143], v160
	ds_read_b128 v[152:155], v160 offset:1024
	ds_read_b128 v[156:159], v160 offset:2048
	ds_read_b128 v[160:163], v160 offset:3072
	ds_read_b128 v[164:167], v176
	ds_read_b128 v[168:171], v176 offset:1024
	ds_read_b128 v[172:175], v176 offset:2048
	ds_read_b128 v[176:179], v176 offset:3072
	s_add_u32 s82, s82, 0x40000
	s_addc_u32 s83, s83, 0
	s_mov_b32 m0, s22
	v_lshl_add_u64 v[252:253], s[82:83], 0, v[96:97]
	ds_read_b128 v[188:191], v151 offset:32768
	ds_read_b128 v[220:223], v151 offset:33792
	ds_read_b128 v[224:227], v151 offset:34816
	ds_read_b128 v[228:231], v151 offset:35840
	ds_read_b128 v[232:235], v151 offset:36864
	ds_read_b128 v[236:239], v151 offset:37888
	ds_read_b128 v[240:243], v151 offset:38912
	ds_read_b128 v[244:247], v151 offset:39936
	global_load_lds_dwordx4 v[252:253], off
	v_lshl_add_u64 v[252:253], s[82:83], 0, v[132:133]
	s_mov_b32 m0, s23
	s_nop 0
	global_load_lds_dwordx4 v[252:253], off
	s_waitcnt vmcnt(8)
	s_waitcnt lgkmcnt(0)
	s_setprio 1
	s_barrier
	v_mfma_f32_16x16x32_bf16 v[128:131], v[140:143], v[188:191], v[128:131]
	v_mfma_f32_16x16x32_bf16 v[120:123], v[156:159], v[188:191], v[120:123]
	v_mfma_f32_16x16x32_bf16 v[112:115], v[140:143], v[224:227], v[112:115]
	v_mfma_f32_16x16x32_bf16 v[104:107], v[156:159], v[224:227], v[104:107]
	v_mfma_f32_16x16x32_bf16 v[92:95], v[140:143], v[232:235], v[92:95]
	v_mfma_f32_16x16x32_bf16 v[84:87], v[156:159], v[232:235], v[84:87]
	v_mfma_f32_16x16x32_bf16 v[76:79], v[140:143], v[240:243], v[76:79]
	v_mfma_f32_16x16x32_bf16 v[68:71], v[156:159], v[240:243], v[68:71]
	v_mfma_f32_16x16x32_bf16 v[128:131], v[152:155], v[220:223], v[128:131]
	v_mfma_f32_16x16x32_bf16 v[120:123], v[160:163], v[220:223], v[120:123]
	v_mfma_f32_16x16x32_bf16 v[112:115], v[152:155], v[228:231], v[112:115]
	v_mfma_f32_16x16x32_bf16 v[104:107], v[160:163], v[228:231], v[104:107]
	v_mfma_f32_16x16x32_bf16 v[92:95], v[152:155], v[236:239], v[92:95]
	v_mfma_f32_16x16x32_bf16 v[84:87], v[160:163], v[236:239], v[84:87]
	v_mfma_f32_16x16x32_bf16 v[76:79], v[152:155], v[244:247], v[76:79]
	v_mfma_f32_16x16x32_bf16 v[68:71], v[160:163], v[244:247], v[68:71]
	v_mfma_f32_16x16x32_bf16 v[124:127], v[164:167], v[188:191], v[124:127]
	v_mfma_f32_16x16x32_bf16 v[116:119], v[172:175], v[188:191], v[116:119]
	v_mfma_f32_16x16x32_bf16 v[108:111], v[164:167], v[224:227], v[108:111]
	v_mfma_f32_16x16x32_bf16 v[100:103], v[172:175], v[224:227], v[100:103]
	v_mfma_f32_16x16x32_bf16 v[88:91], v[164:167], v[232:235], v[88:91]
	v_mfma_f32_16x16x32_bf16 v[80:83], v[172:175], v[232:235], v[80:83]
	v_mfma_f32_16x16x32_bf16 v[72:75], v[164:167], v[240:243], v[72:75]
	v_mfma_f32_16x16x32_bf16 v[64:67], v[172:175], v[240:243], v[64:67]
	v_mfma_f32_16x16x32_bf16 v[124:127], v[168:171], v[220:223], v[124:127]
	v_mfma_f32_16x16x32_bf16 v[116:119], v[176:179], v[220:223], v[116:119]
	v_mfma_f32_16x16x32_bf16 v[108:111], v[168:171], v[228:231], v[108:111]
	v_mfma_f32_16x16x32_bf16 v[100:103], v[176:179], v[228:231], v[100:103]
	v_mfma_f32_16x16x32_bf16 v[88:91], v[168:171], v[236:239], v[88:91]
	v_mfma_f32_16x16x32_bf16 v[80:83], v[176:179], v[236:239], v[80:83]
	v_mfma_f32_16x16x32_bf16 v[72:75], v[168:171], v[244:247], v[72:75]
	v_mfma_f32_16x16x32_bf16 v[64:67], v[176:179], v[244:247], v[64:67]
	s_barrier
	s_setprio 0
	s_add_i32 s82, s85, s10
	v_lshl_add_u64 v[180:181], v[180:181], 0, s[58:59]
	s_mov_b32 m0, s82
	ds_read_b128 v[188:191], v151 offset:49152
	ds_read_b128 v[220:223], v151 offset:50176
	ds_read_b128 v[224:227], v151 offset:51200
	ds_read_b128 v[228:231], v151 offset:52224
	ds_read_b128 v[232:235], v151 offset:53248
	ds_read_b128 v[236:239], v151 offset:54272
	ds_read_b128 v[240:243], v151 offset:55296
	ds_read_b128 v[244:247], v151 offset:56320
	global_load_lds_dwordx4 v[180:181], off
	s_add_i32 m0, s82, 0x2000
	s_add_u32 s80, s80, 0x40080
	v_lshl_add_u64 v[180:181], v[192:193], 0, s[58:59]
	s_addc_u32 s81, s81, 0
	s_add_i32 s82, s86, s10
	global_load_lds_dwordx4 v[180:181], off
	v_lshl_add_u64 v[180:181], s[80:81], 0, v[98:99]
	s_mov_b32 m0, s82
	s_nop 0
	global_load_lds_dwordx4 v[180:181], off
	v_lshl_add_u64 v[180:181], s[80:81], 0, v[134:135]
	s_add_i32 m0, s82, 0x2000
	s_nop 0
	global_load_lds_dwordx4 v[180:181], off
	v_lshl_add_u64 v[180:181], v[248:249], 0, s[58:59]
	s_mov_b32 m0, s33
	s_nop 0
	global_load_lds_dwordx4 v[180:181], off
	v_lshl_add_u64 v[180:181], v[250:251], 0, s[58:59]
	s_mov_b32 m0, s43
	s_nop 0
	global_load_lds_dwordx4 v[180:181], off
	s_waitcnt vmcnt(8)
	s_waitcnt lgkmcnt(0)
	s_setprio 1
	s_barrier
	v_mfma_f32_16x16x32_bf16 v[60:63], v[140:143], v[188:191], v[60:63]
	v_mfma_f32_16x16x32_bf16 v[52:55], v[156:159], v[188:191], v[52:55]
	v_mfma_f32_16x16x32_bf16 v[44:47], v[140:143], v[224:227], v[44:47]
	v_mfma_f32_16x16x32_bf16 v[36:39], v[156:159], v[224:227], v[36:39]
	v_mfma_f32_16x16x32_bf16 v[28:31], v[140:143], v[232:235], v[28:31]
	v_mfma_f32_16x16x32_bf16 v[20:23], v[156:159], v[232:235], v[20:23]
	v_mfma_f32_16x16x32_bf16 v[12:15], v[140:143], v[240:243], v[12:15]
	v_mfma_f32_16x16x32_bf16 v[4:7], v[156:159], v[240:243], v[4:7]
	v_mfma_f32_16x16x32_bf16 v[60:63], v[152:155], v[220:223], v[60:63]
	v_mfma_f32_16x16x32_bf16 v[52:55], v[160:163], v[220:223], v[52:55]
	v_mfma_f32_16x16x32_bf16 v[44:47], v[152:155], v[228:231], v[44:47]
	v_mfma_f32_16x16x32_bf16 v[36:39], v[160:163], v[228:231], v[36:39]
	v_mfma_f32_16x16x32_bf16 v[28:31], v[152:155], v[236:239], v[28:31]
	v_mfma_f32_16x16x32_bf16 v[20:23], v[160:163], v[236:239], v[20:23]
	v_mfma_f32_16x16x32_bf16 v[12:15], v[152:155], v[244:247], v[12:15]
	v_mfma_f32_16x16x32_bf16 v[4:7], v[160:163], v[244:247], v[4:7]
	v_mfma_f32_16x16x32_bf16 v[56:59], v[164:167], v[188:191], v[56:59]
	v_mfma_f32_16x16x32_bf16 v[48:51], v[172:175], v[188:191], v[48:51]
	v_mfma_f32_16x16x32_bf16 v[40:43], v[164:167], v[224:227], v[40:43]
	v_mfma_f32_16x16x32_bf16 v[32:35], v[172:175], v[224:227], v[32:35]
	v_mfma_f32_16x16x32_bf16 v[24:27], v[164:167], v[232:235], v[24:27]
	v_mfma_f32_16x16x32_bf16 v[16:19], v[172:175], v[232:235], v[16:19]
	v_mfma_f32_16x16x32_bf16 v[8:11], v[164:167], v[240:243], v[8:11]
	v_mfma_f32_16x16x32_bf16 v[0:3], v[172:175], v[240:243], v[0:3]
	v_mfma_f32_16x16x32_bf16 v[56:59], v[168:171], v[220:223], v[56:59]
	v_mfma_f32_16x16x32_bf16 v[48:51], v[176:179], v[220:223], v[48:51]
	v_mfma_f32_16x16x32_bf16 v[40:43], v[168:171], v[228:231], v[40:43]
	v_mfma_f32_16x16x32_bf16 v[32:35], v[176:179], v[228:231], v[32:35]
	v_mfma_f32_16x16x32_bf16 v[24:27], v[168:171], v[236:239], v[24:27]
	v_mfma_f32_16x16x32_bf16 v[16:19], v[176:179], v[236:239], v[16:19]
	v_mfma_f32_16x16x32_bf16 v[8:11], v[168:171], v[244:247], v[8:11]
	v_mfma_f32_16x16x32_bf16 v[0:3], v[176:179], v[244:247], v[0:3]
	s_barrier
	s_setprio 0
	s_add_i32 s84, s84, 2
	s_add_u32 s78, s78, 0x100
	s_addc_u32 s79, s79, 0
	s_add_u32 s69, s69, 0x100
	s_addc_u32 s71, s71, 0
	s_cmp_gt_u32 s84, 13
	s_cbranch_scc0 .LBB0_346
